# GEMM k-loops rewritten (3-stage LDS ring, fragment reads software-pipelined under the MFMAs) in all three GEMM variants
# speedup vs baseline: 1.0198x; 1.0113x over previous
; __device__ __forceinline__ int otid() { int t = threadIdx.x; asm volatile("" : "+v"(t)); return t; }
; template <int MODE>
; __device__ void gemm_tile2(const u16* __restrict__ X, int lda, const u16* __restrict__ W, int ldb, int K,
;                            int m0, int n0, u16* __restrict__ outb, int vbase,
;                            const float* resid, float* outf, unsigned char* smem) {
;   u16* sbase = (u16*)smem;
;   const int tid = otid(), lane = tid & 63, l15 = lane & 15, quad = lane >> 4;
;   const int wave = tid >> 6;
;   const int wx = wave >> 1, ww = wave & 1;
;   f32x4 acc[8][4];
; #pragma unroll
;   for (int i = 0; i < 8; ++i)
; #pragma unroll
;     for (int j = 0; j < 4; ++j) acc[i][j] = f32x4{0.f, 0.f, 0.f, 0.f};
;   u32x4 rx[2][4], rw[2][2];
;   const int lrow = tid >> 2, lkc = (tid & 3) * 8;
;   const int lsw = ((tid & 3) ^ ((0 - (lrow >> 2)) & 3)) * 8;
;   const int fsw = (quad ^ ((0 - (l15 >> 2)) & 3)) * 8;
;   const auto rsX = __builtin_amdgcn_make_buffer_rsrc((void*)(X + (size_t)m0 * lda), (short)0, 0x7fffffff, 0x00020000);
;   const auto rsW = __builtin_amdgcn_make_buffer_rsrc((void*)(W + (size_t)n0 * ldb), (short)0, 0x7fffffff, 0x00020000);
;   const int vox = (lrow * lda + lkc) * 2, vow = (lrow * ldb + lkc) * 2;
;   const int nk = K / 32;
;     ...
;   G2_GLOAD(0, 0);
;   G2_GLOAD(1, 1);
;   __syncthreads();
;   G2_LSTORE(0, 0);
;   G2_GLOAD(0, 2);
;   __syncthreads();
;   for (int kt2 = 0; kt2 < nk; kt2 += 2) {
; #pragma unroll
;     for (int h = 0; h < 2; ++h) {
;       const int kt = kt2 + h;
;       const u16* st = sbase + h * G2STAGE;
;       bf16x8 fw[4], fx[4];
; #pragma unroll
;       for (int j = 0; j < 4; ++j) fw[j] = *(const bf16x8*)(st + 256 * G2S + (ww * 64 + j * 16 + l15) * G2S + fsw);
; #pragma unroll
;       for (int i = 0; i < 4; ++i) fx[i] = *(const bf16x8*)(st + (wx * 128 + i * 16 + l15) * G2S + fsw);
;       __builtin_amdgcn_sched_barrier(0);
.LBB0_312:
	v_mov_b32_e32 v0, v210
	s_lshl_b32 s0, s31, 7
	s_lshl_b32 s6, s18, 19
	s_add_u32 s24, s36, s6
	s_addc_u32 s6, s37, 0
	s_and_b32 s25, s6, 0xffff
	s_lshl_b32 s6, s31, 18
	s_add_u32 s40, s8, s6
	s_addc_u32 s6, s9, 0
	s_and_b32 s41, s6, 0xffff
	s_mov_b32 s42, s26
	s_mov_b32 s43, s27
	v_lshlrev_b32_e32 v230, 4, v0
	v_lshrrev_b32_e32 v231, 4, v0
	v_bfe_u32 v233, v0, 6, 1
	v_lshrrev_b32_e32 v2, 2, v0
	v_lshrrev_b32_e32 v3, 4, v0
	v_sub_u32_e32 v4, 0, v3
	v_xor_b32_e32 v4, v0, v4
	v_lshlrev_b32_e32 v4, 4, v4
	v_and_b32_e32 v4, 48, v4
	v_lshl_or_b32 v234, v2, 6, v4
	v_lshlrev_b32_e32 v4, 4, v0
	v_and_b32_e32 v4, 48, v4
	v_lshl_or_b32 v232, v2, 11, v4
	v_sub_u32_e32 v4, 0, v2
	v_xor_b32_e32 v4, v3, v4
	v_lshlrev_b32_e32 v4, 4, v4
	v_and_b32_e32 v4, 48, v4
	v_lshlrev_b32_e32 v5, 6, v0
	v_and_b32_e32 v6, 0x3c0, v5
	v_bfe_u32 v7, v0, 6, 1
	v_lshl_or_b32 v7, v7, 12, v4
	v_add_u32_e32 v235, v7, v6
	v_and_b32_e32 v5, 0xffffe3c0, v5
	v_add_u32_e32 v218, v4, v5
	v_add_u32_e32 v219, 0x6000, v218
	buffer_load_dwordx4 v[2:5], v232, s[24:27], 0 offen
	buffer_load_dwordx4 v[6:9], v232, s[24:27], s27 offen
	buffer_load_dwordx4 v[10:13], v232, s[24:27], s77 offen
	buffer_load_dwordx4 v[14:17], v232, s[24:27], s78 offen
	buffer_load_dwordx4 v[18:21], v232, s[40:43], 0 offen
	buffer_load_dwordx4 v[22:25], v232, s[40:43], s27 offen
	v_add_u32_e32 v232, 64, v232
	buffer_load_dwordx4 v[26:29], v232, s[24:27], 0 offen
	buffer_load_dwordx4 v[30:33], v232, s[24:27], s27 offen
	buffer_load_dwordx4 v[34:37], v232, s[24:27], s77 offen
	buffer_load_dwordx4 v[38:41], v232, s[24:27], s78 offen
	buffer_load_dwordx4 v[42:45], v232, s[40:43], 0 offen
	buffer_load_dwordx4 v[46:49], v232, s[40:43], s27 offen
	v_add_u32_e32 v232, 64, v232
	v_mov_b32_e32 v50, 0
	v_mov_b32_e32 v51, 0
	v_mov_b32_e32 v52, 0
	v_mov_b32_e32 v53, 0
	v_mov_b32_e32 v54, 0
	v_mov_b32_e32 v55, 0
	v_mov_b32_e32 v56, 0
	v_mov_b32_e32 v57, 0
	v_mov_b32_e32 v58, 0
	v_mov_b32_e32 v59, 0
	v_mov_b32_e32 v60, 0
	v_mov_b32_e32 v61, 0
	v_mov_b32_e32 v62, 0
	v_mov_b32_e32 v63, 0
	v_mov_b32_e32 v64, 0
	v_mov_b32_e32 v65, 0
	v_mov_b32_e32 v66, 0
	v_mov_b32_e32 v67, 0
	v_mov_b32_e32 v68, 0
	v_mov_b32_e32 v69, 0
	v_mov_b32_e32 v70, 0
	v_mov_b32_e32 v71, 0
	v_mov_b32_e32 v72, 0
	v_mov_b32_e32 v73, 0
	v_mov_b32_e32 v74, 0
	v_mov_b32_e32 v75, 0
	v_mov_b32_e32 v76, 0
	v_mov_b32_e32 v77, 0
	v_mov_b32_e32 v78, 0
	v_mov_b32_e32 v79, 0
	v_mov_b32_e32 v80, 0
	v_mov_b32_e32 v81, 0
	v_mov_b32_e32 v82, 0
	v_mov_b32_e32 v83, 0
	v_mov_b32_e32 v84, 0
	v_mov_b32_e32 v85, 0
	v_mov_b32_e32 v86, 0
	v_mov_b32_e32 v87, 0
	v_mov_b32_e32 v88, 0
	v_mov_b32_e32 v89, 0
	v_mov_b32_e32 v90, 0
	v_mov_b32_e32 v91, 0
	v_mov_b32_e32 v92, 0
	v_mov_b32_e32 v93, 0
	v_mov_b32_e32 v94, 0
	v_mov_b32_e32 v95, 0
	v_mov_b32_e32 v96, 0
	v_mov_b32_e32 v97, 0
	v_mov_b32_e32 v98, 0
	v_mov_b32_e32 v99, 0
	v_mov_b32_e32 v100, 0
	v_mov_b32_e32 v101, 0
	v_mov_b32_e32 v102, 0
	v_mov_b32_e32 v103, 0
	v_mov_b32_e32 v104, 0
	v_mov_b32_e32 v105, 0
	v_mov_b32_e32 v106, 0
	v_mov_b32_e32 v107, 0
	v_mov_b32_e32 v108, 0
	v_mov_b32_e32 v109, 0
	v_mov_b32_e32 v110, 0
	v_mov_b32_e32 v111, 0
	v_mov_b32_e32 v112, 0
	v_mov_b32_e32 v113, 0
	v_mov_b32_e32 v114, 0
	v_mov_b32_e32 v115, 0
	v_mov_b32_e32 v116, 0
	v_mov_b32_e32 v117, 0
	v_mov_b32_e32 v118, 0
	v_mov_b32_e32 v119, 0
	v_mov_b32_e32 v120, 0
	v_mov_b32_e32 v121, 0
	v_mov_b32_e32 v122, 0
	v_mov_b32_e32 v123, 0
	v_mov_b32_e32 v124, 0
	v_mov_b32_e32 v125, 0
	v_mov_b32_e32 v126, 0
	v_mov_b32_e32 v127, 0
	v_mov_b32_e32 v128, 0
	v_mov_b32_e32 v129, 0
	v_mov_b32_e32 v130, 0
	v_mov_b32_e32 v131, 0
	v_mov_b32_e32 v132, 0
	v_mov_b32_e32 v133, 0
	v_mov_b32_e32 v134, 0
	v_mov_b32_e32 v135, 0
	v_mov_b32_e32 v136, 0
	v_mov_b32_e32 v137, 0
	v_mov_b32_e32 v138, 0
	v_mov_b32_e32 v139, 0
	v_mov_b32_e32 v140, 0
	v_mov_b32_e32 v141, 0
	v_mov_b32_e32 v142, 0
	v_mov_b32_e32 v143, 0
	v_mov_b32_e32 v144, 0
	v_mov_b32_e32 v145, 0
	v_mov_b32_e32 v146, 0
	v_mov_b32_e32 v147, 0
	v_mov_b32_e32 v148, 0
	v_mov_b32_e32 v149, 0
	v_mov_b32_e32 v150, 0
	v_mov_b32_e32 v151, 0
	v_mov_b32_e32 v152, 0
	v_mov_b32_e32 v153, 0
	v_mov_b32_e32 v154, 0
	v_mov_b32_e32 v155, 0
	v_mov_b32_e32 v156, 0
	v_mov_b32_e32 v157, 0
	v_mov_b32_e32 v158, 0
	v_mov_b32_e32 v159, 0
	v_mov_b32_e32 v160, 0
	v_mov_b32_e32 v161, 0
	v_mov_b32_e32 v162, 0
	v_mov_b32_e32 v163, 0
	v_mov_b32_e32 v164, 0
	v_mov_b32_e32 v165, 0
	v_mov_b32_e32 v166, 0
	v_mov_b32_e32 v167, 0
	v_mov_b32_e32 v168, 0
	v_mov_b32_e32 v169, 0
	v_mov_b32_e32 v170, 0
	v_mov_b32_e32 v171, 0
	v_mov_b32_e32 v172, 0
	v_mov_b32_e32 v173, 0
	v_mov_b32_e32 v174, 0
	v_mov_b32_e32 v175, 0
	v_mov_b32_e32 v176, 0
	v_mov_b32_e32 v177, 0
	s_mov_b32 s6, 0x6000
	s_mov_b32 s7, 0x6000
	s_mov_b32 s35, 0xffff4000
	s_mov_b32 s1, 0
	s_barrier
	s_waitcnt vmcnt(6)
	ds_write_b128 v234, v[2:5]
	ds_write_b128 v234, v[6:9] offset:4096
	ds_write_b128 v234, v[10:13] offset:8192
	ds_write_b128 v234, v[14:17] offset:12288
	ds_write_b128 v234, v[18:21] offset:16384
	ds_write_b128 v234, v[22:25] offset:20480
	buffer_load_dwordx4 v[2:5], v232, s[24:27], 0 offen
	buffer_load_dwordx4 v[6:9], v232, s[24:27], s27 offen
	buffer_load_dwordx4 v[10:13], v232, s[24:27], s77 offen
	buffer_load_dwordx4 v[14:17], v232, s[24:27], s78 offen
	buffer_load_dwordx4 v[18:21], v232, s[40:43], 0 offen
	buffer_load_dwordx4 v[22:25], v232, s[40:43], s27 offen
	v_add_u32_e32 v232, 64, v232
	v_add_u32_e32 v234, 0x6000, v234
	s_waitcnt vmcnt(6)
	ds_write_b128 v234, v[26:29]
	ds_write_b128 v234, v[30:33] offset:4096
	ds_write_b128 v234, v[34:37] offset:8192
	ds_write_b128 v234, v[38:41] offset:12288
	ds_write_b128 v234, v[42:45] offset:16384
	ds_write_b128 v234, v[46:49] offset:20480
	buffer_load_dwordx4 v[26:29], v232, s[24:27], 0 offen
	buffer_load_dwordx4 v[30:33], v232, s[24:27], s27 offen
	buffer_load_dwordx4 v[34:37], v232, s[24:27], s77 offen
	buffer_load_dwordx4 v[38:41], v232, s[24:27], s78 offen
	buffer_load_dwordx4 v[42:45], v232, s[40:43], 0 offen
	buffer_load_dwordx4 v[46:49], v232, s[40:43], s27 offen
	v_add_u32_e32 v232, 64, v232
	v_add_u32_e32 v234, 0x6000, v234
	s_waitcnt lgkmcnt(0)
	s_barrier
	ds_read_b128 v[178:181], v235 offset:16384
	ds_read_b128 v[182:185], v235 offset:17408
	ds_read_b128 v[186:189], v235 offset:18432
	ds_read_b128 v[190:193], v235 offset:19456
	v_add_u32_e32 v235, 0x6000, v235
	ds_read_b128 v[194:197], v218
	ds_read_b128 v[198:201], v218 offset:1024
	ds_read_b128 v[202:205], v218 offset:2048
	ds_read_b128 v[206:209], v218 offset:3072
	s_waitcnt lgkmcnt(0)
; template <int MODE>
; __device__ void gemm_tile2(const u16* __restrict__ X, int lda, const u16* __restrict__ W, int ldb, int K,
;                            int m0, int n0, u16* __restrict__ outb, int vbase,
;                            const float* resid, float* outf, unsigned char* smem) {
;     ...
;   G2_GLOAD(0, 0);
;   G2_GLOAD(1, 1);
;   __syncthreads();
;   G2_LSTORE(0, 0);
;   G2_GLOAD(0, 2);
;   __syncthreads();
;   for (int kt2 = 0; kt2 < nk; kt2 += 2) {
; #pragma unroll
;     for (int h = 0; h < 2; ++h) {
;       const int kt = kt2 + h;
;       const u16* st = sbase + h * G2STAGE;
;       bf16x8 fw[4], fx[4];
; #pragma unroll
;       for (int j = 0; j < 4; ++j) fw[j] = *(const bf16x8*)(st + 256 * G2S + (ww * 64 + j * 16 + l15) * G2S + fsw);
; #pragma unroll
;       for (int i = 0; i < 4; ++i) fx[i] = *(const bf16x8*)(st + (wx * 128 + i * 16 + l15) * G2S + fsw);
;       __builtin_amdgcn_sched_barrier(0);
;       __builtin_amdgcn_s_setprio(1);
; #pragma unroll
;       for (int i = 0; i < 4; ++i) {
; #pragma unroll
;         for (int j = 0; j < 4; ++j) {
;           if (MODE == 1) acc[i][j] = mfma16(fx[i], fw[j], acc[i][j]);
;           else acc[i][j] = mfma16(fw[j], fx[i], acc[i][j]);
;         }
;       }
;       __builtin_amdgcn_s_setprio(0);
;       __builtin_amdgcn_sched_barrier(0);
; #pragma unroll
;       for (int i = 0; i < 4; ++i) fx[i] = *(const bf16x8*)(st + (wx * 128 + (i + 4) * 16 + l15) * G2S + fsw);
;       __builtin_amdgcn_sched_barrier(0);
;       if (kt + 1 < nk) G2_LSTORE(1 - h, 1 - h);
;       if (kt + 3 < nk) G2_GLOAD(1 - h, kt + 3);
;       __builtin_amdgcn_sched_barrier(0);
;       __builtin_amdgcn_s_setprio(1);
; #pragma unroll
;       for (int i = 0; i < 4; ++i) {
; #pragma unroll
;         for (int j = 0; j < 4; ++j) {
;           if (MODE == 1) acc[i + 4][j] = mfma16(fx[i], fw[j], acc[i + 4][j]);
;           else acc[i + 4][j] = mfma16(fw[j], fx[i], acc[i + 4][j]);
;         }
;       }
;       __builtin_amdgcn_s_setprio(0);
;       __syncthreads();
;     }
.Lh0_loop:
	v_mfma_f32_16x16x32_bf16 v[174:177], v[178:181], v[194:197], v[174:177]
	v_mfma_f32_16x16x32_bf16 v[170:173], v[182:185], v[194:197], v[170:173]
	v_mfma_f32_16x16x32_bf16 v[166:169], v[186:189], v[194:197], v[166:169]
	v_mfma_f32_16x16x32_bf16 v[162:165], v[190:193], v[194:197], v[162:165]
	ds_read_b128 v[194:197], v218 offset:4096
	ds_read_b128 v[238:241], v235 offset:16384
	v_mfma_f32_16x16x32_bf16 v[158:161], v[178:181], v[198:201], v[158:161]
	v_mfma_f32_16x16x32_bf16 v[154:157], v[182:185], v[198:201], v[154:157]
	v_mfma_f32_16x16x32_bf16 v[150:153], v[186:189], v[198:201], v[150:153]
	v_mfma_f32_16x16x32_bf16 v[146:149], v[190:193], v[198:201], v[146:149]
	ds_read_b128 v[198:201], v218 offset:5120
	ds_read_b128 v[242:245], v235 offset:17408
	v_mfma_f32_16x16x32_bf16 v[142:145], v[178:181], v[202:205], v[142:145]
	v_mfma_f32_16x16x32_bf16 v[138:141], v[182:185], v[202:205], v[138:141]
	v_mfma_f32_16x16x32_bf16 v[134:137], v[186:189], v[202:205], v[134:137]
	v_mfma_f32_16x16x32_bf16 v[130:133], v[190:193], v[202:205], v[130:133]
	ds_read_b128 v[202:205], v218 offset:6144
	ds_read_b128 v[246:249], v235 offset:18432
	s_waitcnt lgkmcnt(6)
	v_mfma_f32_16x16x32_bf16 v[126:129], v[178:181], v[206:209], v[126:129]
	v_mfma_f32_16x16x32_bf16 v[122:125], v[182:185], v[206:209], v[122:125]
	v_mfma_f32_16x16x32_bf16 v[118:121], v[186:189], v[206:209], v[118:121]
	v_mfma_f32_16x16x32_bf16 v[114:117], v[190:193], v[206:209], v[114:117]
	ds_read_b128 v[206:209], v218 offset:7168
	ds_read_b128 v[222:225], v235 offset:19456
	s_add_i32 s38, s6, s7
	v_add_u32_e32 v218, s38, v218
	s_waitcnt lgkmcnt(7)
	v_mfma_f32_16x16x32_bf16 v[110:113], v[178:181], v[194:197], v[110:113]
	v_mfma_f32_16x16x32_bf16 v[106:109], v[182:185], v[194:197], v[106:109]
	v_mfma_f32_16x16x32_bf16 v[102:105], v[186:189], v[194:197], v[102:105]
	v_mfma_f32_16x16x32_bf16 v[98:101], v[190:193], v[194:197], v[98:101]
	ds_read_b128 v[194:197], v219
	s_waitcnt vmcnt(6)
	ds_write_b128 v234, v[2:5]
	ds_write_b128 v234, v[6:9] offset:4096
	s_waitcnt lgkmcnt(8)
	v_mfma_f32_16x16x32_bf16 v[94:97], v[178:181], v[198:201], v[94:97]
	v_mfma_f32_16x16x32_bf16 v[90:93], v[182:185], v[198:201], v[90:93]
	v_mfma_f32_16x16x32_bf16 v[86:89], v[186:189], v[198:201], v[86:89]
	v_mfma_f32_16x16x32_bf16 v[82:85], v[190:193], v[198:201], v[82:85]
	ds_read_b128 v[198:201], v219 offset:1024
	ds_write_b128 v234, v[10:13] offset:8192
	ds_write_b128 v234, v[14:17] offset:12288
	s_waitcnt lgkmcnt(9)
	v_mfma_f32_16x16x32_bf16 v[78:81], v[178:181], v[202:205], v[78:81]
	v_mfma_f32_16x16x32_bf16 v[74:77], v[182:185], v[202:205], v[74:77]
	v_mfma_f32_16x16x32_bf16 v[70:73], v[186:189], v[202:205], v[70:73]
	v_mfma_f32_16x16x32_bf16 v[66:69], v[190:193], v[202:205], v[66:69]
	ds_read_b128 v[202:205], v219 offset:2048
	ds_write_b128 v234, v[18:21] offset:16384
	ds_write_b128 v234, v[22:25] offset:20480
	v_add_u32_e32 v234, s35, v234
	s_waitcnt lgkmcnt(10)
	v_mfma_f32_16x16x32_bf16 v[62:65], v[178:181], v[206:209], v[62:65]
	v_mfma_f32_16x16x32_bf16 v[58:61], v[182:185], v[206:209], v[58:61]
	v_mfma_f32_16x16x32_bf16 v[54:57], v[186:189], v[206:209], v[54:57]
	v_mfma_f32_16x16x32_bf16 v[50:53], v[190:193], v[206:209], v[50:53]
	ds_read_b128 v[206:209], v219 offset:3072
	v_add_u32_e32 v235, s7, v235
	buffer_load_dwordx4 v[2:5], v232, s[24:27], 0 offen
	buffer_load_dwordx4 v[6:9], v232, s[24:27], s27 offen
	buffer_load_dwordx4 v[10:13], v232, s[24:27], s77 offen
	buffer_load_dwordx4 v[14:17], v232, s[24:27], s78 offen
	buffer_load_dwordx4 v[18:21], v232, s[40:43], 0 offen
	buffer_load_dwordx4 v[22:25], v232, s[40:43], s27 offen
	v_add_u32_e32 v232, 64, v232
	s_waitcnt lgkmcnt(1)
	s_barrier
	s_mov_b32 s38, s6
	s_mov_b32 s6, s7
	s_mov_b32 s7, s35
	s_mov_b32 s35, s38
	v_mfma_f32_16x16x32_bf16 v[174:177], v[238:241], v[194:197], v[174:177]
	v_mfma_f32_16x16x32_bf16 v[170:173], v[242:245], v[194:197], v[170:173]
	v_mfma_f32_16x16x32_bf16 v[166:169], v[246:249], v[194:197], v[166:169]
	v_mfma_f32_16x16x32_bf16 v[162:165], v[222:225], v[194:197], v[162:165]
	ds_read_b128 v[194:197], v219 offset:4096
	ds_read_b128 v[178:181], v235 offset:16384
	v_mfma_f32_16x16x32_bf16 v[158:161], v[238:241], v[198:201], v[158:161]
	v_mfma_f32_16x16x32_bf16 v[154:157], v[242:245], v[198:201], v[154:157]
	v_mfma_f32_16x16x32_bf16 v[150:153], v[246:249], v[198:201], v[150:153]
	v_mfma_f32_16x16x32_bf16 v[146:149], v[222:225], v[198:201], v[146:149]
	ds_read_b128 v[198:201], v219 offset:5120
	ds_read_b128 v[182:185], v235 offset:17408
	v_mfma_f32_16x16x32_bf16 v[142:145], v[238:241], v[202:205], v[142:145]
	v_mfma_f32_16x16x32_bf16 v[138:141], v[242:245], v[202:205], v[138:141]
	v_mfma_f32_16x16x32_bf16 v[134:137], v[246:249], v[202:205], v[134:137]
	v_mfma_f32_16x16x32_bf16 v[130:133], v[222:225], v[202:205], v[130:133]
	ds_read_b128 v[202:205], v219 offset:6144
	ds_read_b128 v[186:189], v235 offset:18432
	s_waitcnt lgkmcnt(6)
	v_mfma_f32_16x16x32_bf16 v[126:129], v[238:241], v[206:209], v[126:129]
	v_mfma_f32_16x16x32_bf16 v[122:125], v[242:245], v[206:209], v[122:125]
	v_mfma_f32_16x16x32_bf16 v[118:121], v[246:249], v[206:209], v[118:121]
	v_mfma_f32_16x16x32_bf16 v[114:117], v[222:225], v[206:209], v[114:117]
	ds_read_b128 v[206:209], v219 offset:7168
	ds_read_b128 v[190:193], v235 offset:19456
	s_add_i32 s38, s6, s7
	v_add_u32_e32 v219, s38, v219
	s_waitcnt lgkmcnt(7)
	v_mfma_f32_16x16x32_bf16 v[110:113], v[238:241], v[194:197], v[110:113]
	v_mfma_f32_16x16x32_bf16 v[106:109], v[242:245], v[194:197], v[106:109]
	v_mfma_f32_16x16x32_bf16 v[102:105], v[246:249], v[194:197], v[102:105]
	v_mfma_f32_16x16x32_bf16 v[98:101], v[222:225], v[194:197], v[98:101]
	ds_read_b128 v[194:197], v218
	s_waitcnt vmcnt(6)
; template <int MODE>
; __device__ void gemm_tile2(const u16* __restrict__ X, int lda, const u16* __restrict__ W, int ldb, int K,
;                            int m0, int n0, u16* __restrict__ outb, int vbase,
;                            const float* resid, float* outf, unsigned char* smem) {
;     ...
;   G2_GLOAD(0, 0);
;   G2_GLOAD(1, 1);
;   __syncthreads();
;   G2_LSTORE(0, 0);
;   G2_GLOAD(0, 2);
;   __syncthreads();
;   for (int kt2 = 0; kt2 < nk; kt2 += 2) {
; #pragma unroll
;     for (int h = 0; h < 2; ++h) {
;       const int kt = kt2 + h;
;       const u16* st = sbase + h * G2STAGE;
;       bf16x8 fw[4], fx[4];
; #pragma unroll
;       for (int j = 0; j < 4; ++j) fw[j] = *(const bf16x8*)(st + 256 * G2S + (ww * 64 + j * 16 + l15) * G2S + fsw);
; #pragma unroll
;       for (int i = 0; i < 4; ++i) fx[i] = *(const bf16x8*)(st + (wx * 128 + i * 16 + l15) * G2S + fsw);
;       __builtin_amdgcn_sched_barrier(0);
;       __builtin_amdgcn_s_setprio(1);
; #pragma unroll
;       for (int i = 0; i < 4; ++i) {
; #pragma unroll
;         for (int j = 0; j < 4; ++j) {
;           if (MODE == 1) acc[i][j] = mfma16(fx[i], fw[j], acc[i][j]);
;           else acc[i][j] = mfma16(fw[j], fx[i], acc[i][j]);
;         }
;       }
;       __builtin_amdgcn_s_setprio(0);
;       __builtin_amdgcn_sched_barrier(0);
; #pragma unroll
;       for (int i = 0; i < 4; ++i) fx[i] = *(const bf16x8*)(st + (wx * 128 + (i + 4) * 16 + l15) * G2S + fsw);
;       __builtin_amdgcn_sched_barrier(0);
;       if (kt + 1 < nk) G2_LSTORE(1 - h, 1 - h);
;       if (kt + 3 < nk) G2_GLOAD(1 - h, kt + 3);
;       __builtin_amdgcn_sched_barrier(0);
;       __builtin_amdgcn_s_setprio(1);
; #pragma unroll
;       for (int i = 0; i < 4; ++i) {
; #pragma unroll
;         for (int j = 0; j < 4; ++j) {
;           if (MODE == 1) acc[i + 4][j] = mfma16(fx[i], fw[j], acc[i + 4][j]);
;           else acc[i + 4][j] = mfma16(fw[j], fx[i], acc[i + 4][j]);
;         }
;       }
;       __builtin_amdgcn_s_setprio(0);
;       __syncthreads();
;     }
	ds_write_b128 v234, v[26:29]
	ds_write_b128 v234, v[30:33] offset:4096
	s_waitcnt lgkmcnt(8)
	v_mfma_f32_16x16x32_bf16 v[94:97], v[238:241], v[198:201], v[94:97]
	v_mfma_f32_16x16x32_bf16 v[90:93], v[242:245], v[198:201], v[90:93]
	v_mfma_f32_16x16x32_bf16 v[86:89], v[246:249], v[198:201], v[86:89]
	v_mfma_f32_16x16x32_bf16 v[82:85], v[222:225], v[198:201], v[82:85]
	ds_read_b128 v[198:201], v218 offset:1024
	ds_write_b128 v234, v[34:37] offset:8192
	ds_write_b128 v234, v[38:41] offset:12288
	s_waitcnt lgkmcnt(9)
	v_mfma_f32_16x16x32_bf16 v[78:81], v[238:241], v[202:205], v[78:81]
	v_mfma_f32_16x16x32_bf16 v[74:77], v[242:245], v[202:205], v[74:77]
	v_mfma_f32_16x16x32_bf16 v[70:73], v[246:249], v[202:205], v[70:73]
	v_mfma_f32_16x16x32_bf16 v[66:69], v[222:225], v[202:205], v[66:69]
	ds_read_b128 v[202:205], v218 offset:2048
	ds_write_b128 v234, v[42:45] offset:16384
	ds_write_b128 v234, v[46:49] offset:20480
	v_add_u32_e32 v234, s35, v234
	s_waitcnt lgkmcnt(10)
	v_mfma_f32_16x16x32_bf16 v[62:65], v[238:241], v[206:209], v[62:65]
	v_mfma_f32_16x16x32_bf16 v[58:61], v[242:245], v[206:209], v[58:61]
	v_mfma_f32_16x16x32_bf16 v[54:57], v[246:249], v[206:209], v[54:57]
	v_mfma_f32_16x16x32_bf16 v[50:53], v[222:225], v[206:209], v[50:53]
	ds_read_b128 v[206:209], v218 offset:3072
	v_add_u32_e32 v235, s7, v235
	buffer_load_dwordx4 v[26:29], v232, s[24:27], 0 offen
	buffer_load_dwordx4 v[30:33], v232, s[24:27], s27 offen
	buffer_load_dwordx4 v[34:37], v232, s[24:27], s77 offen
	buffer_load_dwordx4 v[38:41], v232, s[24:27], s78 offen
	buffer_load_dwordx4 v[42:45], v232, s[40:43], 0 offen
	buffer_load_dwordx4 v[46:49], v232, s[40:43], s27 offen
	v_add_u32_e32 v232, 64, v232
	s_waitcnt lgkmcnt(1)
	s_barrier
	s_mov_b32 s38, s6
	s_mov_b32 s6, s7
	s_mov_b32 s7, s35
	s_mov_b32 s35, s38
	s_add_u32 s1, s1, 2
	s_cmp_lt_u32 s1, 28
	s_cbranch_scc1 .Lh0_loop
	v_mfma_f32_16x16x32_bf16 v[174:177], v[178:181], v[194:197], v[174:177]
	v_mfma_f32_16x16x32_bf16 v[170:173], v[182:185], v[194:197], v[170:173]
	v_mfma_f32_16x16x32_bf16 v[166:169], v[186:189], v[194:197], v[166:169]
	v_mfma_f32_16x16x32_bf16 v[162:165], v[190:193], v[194:197], v[162:165]
	ds_read_b128 v[194:197], v218 offset:4096
	ds_read_b128 v[238:241], v235 offset:16384
	v_mfma_f32_16x16x32_bf16 v[158:161], v[178:181], v[198:201], v[158:161]
	v_mfma_f32_16x16x32_bf16 v[154:157], v[182:185], v[198:201], v[154:157]
	v_mfma_f32_16x16x32_bf16 v[150:153], v[186:189], v[198:201], v[150:153]
	v_mfma_f32_16x16x32_bf16 v[146:149], v[190:193], v[198:201], v[146:149]
	ds_read_b128 v[198:201], v218 offset:5120
	ds_read_b128 v[242:245], v235 offset:17408
	v_mfma_f32_16x16x32_bf16 v[142:145], v[178:181], v[202:205], v[142:145]
	v_mfma_f32_16x16x32_bf16 v[138:141], v[182:185], v[202:205], v[138:141]
	v_mfma_f32_16x16x32_bf16 v[134:137], v[186:189], v[202:205], v[134:137]
	v_mfma_f32_16x16x32_bf16 v[130:133], v[190:193], v[202:205], v[130:133]
	ds_read_b128 v[202:205], v218 offset:6144
	ds_read_b128 v[246:249], v235 offset:18432
	s_waitcnt lgkmcnt(6)
	v_mfma_f32_16x16x32_bf16 v[126:129], v[178:181], v[206:209], v[126:129]
	v_mfma_f32_16x16x32_bf16 v[122:125], v[182:185], v[206:209], v[122:125]
	v_mfma_f32_16x16x32_bf16 v[118:121], v[186:189], v[206:209], v[118:121]
	v_mfma_f32_16x16x32_bf16 v[114:117], v[190:193], v[206:209], v[114:117]
	ds_read_b128 v[206:209], v218 offset:7168
	ds_read_b128 v[222:225], v235 offset:19456
	s_add_i32 s38, s6, s7
	v_add_u32_e32 v218, s38, v218
	s_waitcnt lgkmcnt(7)
	v_mfma_f32_16x16x32_bf16 v[110:113], v[178:181], v[194:197], v[110:113]
	v_mfma_f32_16x16x32_bf16 v[106:109], v[182:185], v[194:197], v[106:109]
	v_mfma_f32_16x16x32_bf16 v[102:105], v[186:189], v[194:197], v[102:105]
	v_mfma_f32_16x16x32_bf16 v[98:101], v[190:193], v[194:197], v[98:101]
	ds_read_b128 v[194:197], v219
	s_waitcnt vmcnt(6)
	ds_write_b128 v234, v[2:5]
	ds_write_b128 v234, v[6:9] offset:4096
	s_waitcnt lgkmcnt(8)
	v_mfma_f32_16x16x32_bf16 v[94:97], v[178:181], v[198:201], v[94:97]
	v_mfma_f32_16x16x32_bf16 v[90:93], v[182:185], v[198:201], v[90:93]
	v_mfma_f32_16x16x32_bf16 v[86:89], v[186:189], v[198:201], v[86:89]
	v_mfma_f32_16x16x32_bf16 v[82:85], v[190:193], v[198:201], v[82:85]
	ds_read_b128 v[198:201], v219 offset:1024
	ds_write_b128 v234, v[10:13] offset:8192
	ds_write_b128 v234, v[14:17] offset:12288
	s_waitcnt lgkmcnt(9)
	v_mfma_f32_16x16x32_bf16 v[78:81], v[178:181], v[202:205], v[78:81]
	v_mfma_f32_16x16x32_bf16 v[74:77], v[182:185], v[202:205], v[74:77]
	v_mfma_f32_16x16x32_bf16 v[70:73], v[186:189], v[202:205], v[70:73]
	v_mfma_f32_16x16x32_bf16 v[66:69], v[190:193], v[202:205], v[66:69]
	ds_read_b128 v[202:205], v219 offset:2048
	ds_write_b128 v234, v[18:21] offset:16384
	ds_write_b128 v234, v[22:25] offset:20480
	v_add_u32_e32 v234, s35, v234
	s_waitcnt lgkmcnt(10)
	v_mfma_f32_16x16x32_bf16 v[62:65], v[178:181], v[206:209], v[62:65]
	v_mfma_f32_16x16x32_bf16 v[58:61], v[182:185], v[206:209], v[58:61]
	v_mfma_f32_16x16x32_bf16 v[54:57], v[186:189], v[206:209], v[54:57]
	v_mfma_f32_16x16x32_bf16 v[50:53], v[190:193], v[206:209], v[50:53]
	ds_read_b128 v[206:209], v219 offset:3072
	v_add_u32_e32 v235, s7, v235
	s_waitcnt lgkmcnt(1)
	s_barrier
; template <int MODE>
; __device__ void gemm_tile2(const u16* __restrict__ X, int lda, const u16* __restrict__ W, int ldb, int K,
;                            int m0, int n0, u16* __restrict__ outb, int vbase,
;                            const float* resid, float* outf, unsigned char* smem) {
;     ...
;   G2_GLOAD(0, 0);
;   G2_GLOAD(1, 1);
;   __syncthreads();
;   G2_LSTORE(0, 0);
;   G2_GLOAD(0, 2);
;   __syncthreads();
;   for (int kt2 = 0; kt2 < nk; kt2 += 2) {
; #pragma unroll
;     for (int h = 0; h < 2; ++h) {
;       const int kt = kt2 + h;
;       const u16* st = sbase + h * G2STAGE;
;       bf16x8 fw[4], fx[4];
; #pragma unroll
;       for (int j = 0; j < 4; ++j) fw[j] = *(const bf16x8*)(st + 256 * G2S + (ww * 64 + j * 16 + l15) * G2S + fsw);
; #pragma unroll
;       for (int i = 0; i < 4; ++i) fx[i] = *(const bf16x8*)(st + (wx * 128 + i * 16 + l15) * G2S + fsw);
;       __builtin_amdgcn_sched_barrier(0);
;       __builtin_amdgcn_s_setprio(1);
; #pragma unroll
;       for (int i = 0; i < 4; ++i) {
; #pragma unroll
;         for (int j = 0; j < 4; ++j) {
;           if (MODE == 1) acc[i][j] = mfma16(fx[i], fw[j], acc[i][j]);
;           else acc[i][j] = mfma16(fw[j], fx[i], acc[i][j]);
;         }
;       }
;       __builtin_amdgcn_s_setprio(0);
;       __builtin_amdgcn_sched_barrier(0);
; #pragma unroll
;       for (int i = 0; i < 4; ++i) fx[i] = *(const bf16x8*)(st + (wx * 128 + (i + 4) * 16 + l15) * G2S + fsw);
;       __builtin_amdgcn_sched_barrier(0);
;       if (kt + 1 < nk) G2_LSTORE(1 - h, 1 - h);
;       if (kt + 3 < nk) G2_GLOAD(1 - h, kt + 3);
;       __builtin_amdgcn_sched_barrier(0);
;       __builtin_amdgcn_s_setprio(1);
; #pragma unroll
;       for (int i = 0; i < 4; ++i) {
; #pragma unroll
;         for (int j = 0; j < 4; ++j) {
;           if (MODE == 1) acc[i + 4][j] = mfma16(fx[i], fw[j], acc[i + 4][j]);
;           else acc[i + 4][j] = mfma16(fw[j], fx[i], acc[i + 4][j]);
;         }
;       }
;       __builtin_amdgcn_s_setprio(0);
;       __syncthreads();
;     }
	s_mov_b32 s38, s6
	s_mov_b32 s6, s7
	s_mov_b32 s7, s35
	s_mov_b32 s35, s38
	v_mfma_f32_16x16x32_bf16 v[174:177], v[238:241], v[194:197], v[174:177]
	v_mfma_f32_16x16x32_bf16 v[170:173], v[242:245], v[194:197], v[170:173]
	v_mfma_f32_16x16x32_bf16 v[166:169], v[246:249], v[194:197], v[166:169]
	v_mfma_f32_16x16x32_bf16 v[162:165], v[222:225], v[194:197], v[162:165]
	ds_read_b128 v[194:197], v219 offset:4096
	ds_read_b128 v[178:181], v235 offset:16384
	v_mfma_f32_16x16x32_bf16 v[158:161], v[238:241], v[198:201], v[158:161]
	v_mfma_f32_16x16x32_bf16 v[154:157], v[242:245], v[198:201], v[154:157]
	v_mfma_f32_16x16x32_bf16 v[150:153], v[246:249], v[198:201], v[150:153]
	v_mfma_f32_16x16x32_bf16 v[146:149], v[222:225], v[198:201], v[146:149]
	ds_read_b128 v[198:201], v219 offset:5120
	ds_read_b128 v[182:185], v235 offset:17408
	v_mfma_f32_16x16x32_bf16 v[142:145], v[238:241], v[202:205], v[142:145]
	v_mfma_f32_16x16x32_bf16 v[138:141], v[242:245], v[202:205], v[138:141]
	v_mfma_f32_16x16x32_bf16 v[134:137], v[246:249], v[202:205], v[134:137]
	v_mfma_f32_16x16x32_bf16 v[130:133], v[222:225], v[202:205], v[130:133]
	ds_read_b128 v[202:205], v219 offset:6144
	ds_read_b128 v[186:189], v235 offset:18432
	s_waitcnt lgkmcnt(6)
	v_mfma_f32_16x16x32_bf16 v[126:129], v[238:241], v[206:209], v[126:129]
	v_mfma_f32_16x16x32_bf16 v[122:125], v[242:245], v[206:209], v[122:125]
	v_mfma_f32_16x16x32_bf16 v[118:121], v[246:249], v[206:209], v[118:121]
	v_mfma_f32_16x16x32_bf16 v[114:117], v[222:225], v[206:209], v[114:117]
	ds_read_b128 v[206:209], v219 offset:7168
	ds_read_b128 v[190:193], v235 offset:19456
	s_add_i32 s38, s6, s7
	v_add_u32_e32 v219, s38, v219
	s_waitcnt lgkmcnt(7)
	v_mfma_f32_16x16x32_bf16 v[110:113], v[238:241], v[194:197], v[110:113]
	v_mfma_f32_16x16x32_bf16 v[106:109], v[242:245], v[194:197], v[106:109]
	v_mfma_f32_16x16x32_bf16 v[102:105], v[246:249], v[194:197], v[102:105]
	v_mfma_f32_16x16x32_bf16 v[98:101], v[222:225], v[194:197], v[98:101]
	ds_read_b128 v[194:197], v218
	s_waitcnt vmcnt(0)
	ds_write_b128 v234, v[26:29]
	ds_write_b128 v234, v[30:33] offset:4096
	s_waitcnt lgkmcnt(8)
	v_mfma_f32_16x16x32_bf16 v[94:97], v[238:241], v[198:201], v[94:97]
	v_mfma_f32_16x16x32_bf16 v[90:93], v[242:245], v[198:201], v[90:93]
	v_mfma_f32_16x16x32_bf16 v[86:89], v[246:249], v[198:201], v[86:89]
	v_mfma_f32_16x16x32_bf16 v[82:85], v[222:225], v[198:201], v[82:85]
	ds_read_b128 v[198:201], v218 offset:1024
	ds_write_b128 v234, v[34:37] offset:8192
	ds_write_b128 v234, v[38:41] offset:12288
	s_waitcnt lgkmcnt(9)
	v_mfma_f32_16x16x32_bf16 v[78:81], v[238:241], v[202:205], v[78:81]
	v_mfma_f32_16x16x32_bf16 v[74:77], v[242:245], v[202:205], v[74:77]
	v_mfma_f32_16x16x32_bf16 v[70:73], v[246:249], v[202:205], v[70:73]
	v_mfma_f32_16x16x32_bf16 v[66:69], v[222:225], v[202:205], v[66:69]
	ds_read_b128 v[202:205], v218 offset:2048
	ds_write_b128 v234, v[42:45] offset:16384
	ds_write_b128 v234, v[46:49] offset:20480
	v_add_u32_e32 v234, s35, v234
	s_waitcnt lgkmcnt(10)
	v_mfma_f32_16x16x32_bf16 v[62:65], v[238:241], v[206:209], v[62:65]
	v_mfma_f32_16x16x32_bf16 v[58:61], v[242:245], v[206:209], v[58:61]
	v_mfma_f32_16x16x32_bf16 v[54:57], v[246:249], v[206:209], v[54:57]
	v_mfma_f32_16x16x32_bf16 v[50:53], v[222:225], v[206:209], v[50:53]
	ds_read_b128 v[206:209], v218 offset:3072
	v_add_u32_e32 v235, s7, v235
	s_waitcnt lgkmcnt(1)
	s_barrier
; template <int MODE>
; __device__ void gemm_tile2(const u16* __restrict__ X, int lda, const u16* __restrict__ W, int ldb, int K,
;                            int m0, int n0, u16* __restrict__ outb, int vbase,
;                            const float* resid, float* outf, unsigned char* smem) {
;     ...
;   G2_GLOAD(0, 0);
;   G2_GLOAD(1, 1);
;   __syncthreads();
;   G2_LSTORE(0, 0);
;   G2_GLOAD(0, 2);
;   __syncthreads();
;   for (int kt2 = 0; kt2 < nk; kt2 += 2) {
; #pragma unroll
;     for (int h = 0; h < 2; ++h) {
;       const int kt = kt2 + h;
;       const u16* st = sbase + h * G2STAGE;
;       bf16x8 fw[4], fx[4];
; #pragma unroll
;       for (int j = 0; j < 4; ++j) fw[j] = *(const bf16x8*)(st + 256 * G2S + (ww * 64 + j * 16 + l15) * G2S + fsw);
; #pragma unroll
;       for (int i = 0; i < 4; ++i) fx[i] = *(const bf16x8*)(st + (wx * 128 + i * 16 + l15) * G2S + fsw);
;       __builtin_amdgcn_sched_barrier(0);
;       __builtin_amdgcn_s_setprio(1);
; #pragma unroll
;       for (int i = 0; i < 4; ++i) {
; #pragma unroll
;         for (int j = 0; j < 4; ++j) {
;           if (MODE == 1) acc[i][j] = mfma16(fx[i], fw[j], acc[i][j]);
;           else acc[i][j] = mfma16(fw[j], fx[i], acc[i][j]);
;         }
;       }
;       __builtin_amdgcn_s_setprio(0);
;       __builtin_amdgcn_sched_barrier(0);
; #pragma unroll
;       for (int i = 0; i < 4; ++i) fx[i] = *(const bf16x8*)(st + (wx * 128 + (i + 4) * 16 + l15) * G2S + fsw);
;       __builtin_amdgcn_sched_barrier(0);
;       if (kt + 1 < nk) G2_LSTORE(1 - h, 1 - h);
;       if (kt + 3 < nk) G2_GLOAD(1 - h, kt + 3);
;       __builtin_amdgcn_sched_barrier(0);
;       __builtin_amdgcn_s_setprio(1);
; #pragma unroll
;       for (int i = 0; i < 4; ++i) {
; #pragma unroll
;         for (int j = 0; j < 4; ++j) {
;           if (MODE == 1) acc[i + 4][j] = mfma16(fx[i], fw[j], acc[i + 4][j]);
;           else acc[i + 4][j] = mfma16(fw[j], fx[i], acc[i + 4][j]);
;         }
;       }
;       __builtin_amdgcn_s_setprio(0);
;       __syncthreads();
;     }
	s_mov_b32 s38, s6
	s_mov_b32 s6, s7
	s_mov_b32 s7, s35
	s_mov_b32 s35, s38
	v_mfma_f32_16x16x32_bf16 v[174:177], v[178:181], v[194:197], v[174:177]
	v_mfma_f32_16x16x32_bf16 v[170:173], v[182:185], v[194:197], v[170:173]
	v_mfma_f32_16x16x32_bf16 v[166:169], v[186:189], v[194:197], v[166:169]
	v_mfma_f32_16x16x32_bf16 v[162:165], v[190:193], v[194:197], v[162:165]
	ds_read_b128 v[194:197], v218 offset:4096
	ds_read_b128 v[238:241], v235 offset:16384
	v_mfma_f32_16x16x32_bf16 v[158:161], v[178:181], v[198:201], v[158:161]
	v_mfma_f32_16x16x32_bf16 v[154:157], v[182:185], v[198:201], v[154:157]
	v_mfma_f32_16x16x32_bf16 v[150:153], v[186:189], v[198:201], v[150:153]
	v_mfma_f32_16x16x32_bf16 v[146:149], v[190:193], v[198:201], v[146:149]
	ds_read_b128 v[198:201], v218 offset:5120
	ds_read_b128 v[242:245], v235 offset:17408
	v_mfma_f32_16x16x32_bf16 v[142:145], v[178:181], v[202:205], v[142:145]
	v_mfma_f32_16x16x32_bf16 v[138:141], v[182:185], v[202:205], v[138:141]
	v_mfma_f32_16x16x32_bf16 v[134:137], v[186:189], v[202:205], v[134:137]
	v_mfma_f32_16x16x32_bf16 v[130:133], v[190:193], v[202:205], v[130:133]
	ds_read_b128 v[202:205], v218 offset:6144
	ds_read_b128 v[246:249], v235 offset:18432
	s_waitcnt lgkmcnt(6)
	v_mfma_f32_16x16x32_bf16 v[126:129], v[178:181], v[206:209], v[126:129]
	v_mfma_f32_16x16x32_bf16 v[122:125], v[182:185], v[206:209], v[122:125]
	v_mfma_f32_16x16x32_bf16 v[118:121], v[186:189], v[206:209], v[118:121]
	v_mfma_f32_16x16x32_bf16 v[114:117], v[190:193], v[206:209], v[114:117]
	ds_read_b128 v[206:209], v218 offset:7168
	ds_read_b128 v[222:225], v235 offset:19456
	s_add_i32 s38, s6, s7
	v_add_u32_e32 v218, s38, v218
	s_waitcnt lgkmcnt(7)
	v_mfma_f32_16x16x32_bf16 v[110:113], v[178:181], v[194:197], v[110:113]
	v_mfma_f32_16x16x32_bf16 v[106:109], v[182:185], v[194:197], v[106:109]
	v_mfma_f32_16x16x32_bf16 v[102:105], v[186:189], v[194:197], v[102:105]
	v_mfma_f32_16x16x32_bf16 v[98:101], v[190:193], v[194:197], v[98:101]
	ds_read_b128 v[194:197], v219
	s_waitcnt lgkmcnt(6)
	v_mfma_f32_16x16x32_bf16 v[94:97], v[178:181], v[198:201], v[94:97]
	v_mfma_f32_16x16x32_bf16 v[90:93], v[182:185], v[198:201], v[90:93]
	v_mfma_f32_16x16x32_bf16 v[86:89], v[186:189], v[198:201], v[86:89]
	v_mfma_f32_16x16x32_bf16 v[82:85], v[190:193], v[198:201], v[82:85]
	ds_read_b128 v[198:201], v219 offset:1024
	s_waitcnt lgkmcnt(5)
	v_mfma_f32_16x16x32_bf16 v[78:81], v[178:181], v[202:205], v[78:81]
	v_mfma_f32_16x16x32_bf16 v[74:77], v[182:185], v[202:205], v[74:77]
	v_mfma_f32_16x16x32_bf16 v[70:73], v[186:189], v[202:205], v[70:73]
	v_mfma_f32_16x16x32_bf16 v[66:69], v[190:193], v[202:205], v[66:69]
	ds_read_b128 v[202:205], v219 offset:2048
	s_waitcnt lgkmcnt(4)
	v_mfma_f32_16x16x32_bf16 v[62:65], v[178:181], v[206:209], v[62:65]
	v_mfma_f32_16x16x32_bf16 v[58:61], v[182:185], v[206:209], v[58:61]
	v_mfma_f32_16x16x32_bf16 v[54:57], v[186:189], v[206:209], v[54:57]
	v_mfma_f32_16x16x32_bf16 v[50:53], v[190:193], v[206:209], v[50:53]
	ds_read_b128 v[206:209], v219 offset:3072
	v_add_u32_e32 v235, s7, v235
	s_waitcnt lgkmcnt(1)
	s_barrier
	s_mov_b32 s38, s6
	s_mov_b32 s6, s7
	s_mov_b32 s7, s35
	s_mov_b32 s35, s38
	v_mfma_f32_16x16x32_bf16 v[174:177], v[238:241], v[194:197], v[174:177]
	v_mfma_f32_16x16x32_bf16 v[170:173], v[242:245], v[194:197], v[170:173]
	v_mfma_f32_16x16x32_bf16 v[166:169], v[246:249], v[194:197], v[166:169]
	v_mfma_f32_16x16x32_bf16 v[162:165], v[222:225], v[194:197], v[162:165]
	ds_read_b128 v[194:197], v219 offset:4096
	v_mfma_f32_16x16x32_bf16 v[158:161], v[238:241], v[198:201], v[158:161]
	v_mfma_f32_16x16x32_bf16 v[154:157], v[242:245], v[198:201], v[154:157]
	v_mfma_f32_16x16x32_bf16 v[150:153], v[246:249], v[198:201], v[150:153]
	v_mfma_f32_16x16x32_bf16 v[146:149], v[222:225], v[198:201], v[146:149]
	ds_read_b128 v[198:201], v219 offset:5120
	v_mfma_f32_16x16x32_bf16 v[142:145], v[238:241], v[202:205], v[142:145]
	v_mfma_f32_16x16x32_bf16 v[138:141], v[242:245], v[202:205], v[138:141]
	v_mfma_f32_16x16x32_bf16 v[134:137], v[246:249], v[202:205], v[134:137]
	v_mfma_f32_16x16x32_bf16 v[130:133], v[222:225], v[202:205], v[130:133]
	ds_read_b128 v[202:205], v219 offset:6144
	s_waitcnt lgkmcnt(3)
	v_mfma_f32_16x16x32_bf16 v[126:129], v[238:241], v[206:209], v[126:129]
	v_mfma_f32_16x16x32_bf16 v[122:125], v[242:245], v[206:209], v[122:125]
	v_mfma_f32_16x16x32_bf16 v[118:121], v[246:249], v[206:209], v[118:121]
	v_mfma_f32_16x16x32_bf16 v[114:117], v[222:225], v[206:209], v[114:117]
	ds_read_b128 v[206:209], v219 offset:7168
	s_add_i32 s38, s6, s7
	v_add_u32_e32 v219, s38, v219
	s_waitcnt lgkmcnt(3)
	v_mfma_f32_16x16x32_bf16 v[110:113], v[238:241], v[194:197], v[110:113]
	v_mfma_f32_16x16x32_bf16 v[106:109], v[242:245], v[194:197], v[106:109]
	v_mfma_f32_16x16x32_bf16 v[102:105], v[246:249], v[194:197], v[102:105]
	v_mfma_f32_16x16x32_bf16 v[98:101], v[222:225], v[194:197], v[98:101]
	s_waitcnt lgkmcnt(2)
	v_mfma_f32_16x16x32_bf16 v[94:97], v[238:241], v[198:201], v[94:97]
	v_mfma_f32_16x16x32_bf16 v[90:93], v[242:245], v[198:201], v[90:93]
	v_mfma_f32_16x16x32_bf16 v[86:89], v[246:249], v[198:201], v[86:89]
	v_mfma_f32_16x16x32_bf16 v[82:85], v[222:225], v[198:201], v[82:85]
	s_waitcnt lgkmcnt(1)
	v_mfma_f32_16x16x32_bf16 v[78:81], v[238:241], v[202:205], v[78:81]
	v_mfma_f32_16x16x32_bf16 v[74:77], v[242:245], v[202:205], v[74:77]
	v_mfma_f32_16x16x32_bf16 v[70:73], v[246:249], v[202:205], v[70:73]
	v_mfma_f32_16x16x32_bf16 v[66:69], v[222:225], v[202:205], v[66:69]
	s_waitcnt lgkmcnt(0)
	v_mfma_f32_16x16x32_bf16 v[62:65], v[238:241], v[206:209], v[62:65]
	v_mfma_f32_16x16x32_bf16 v[58:61], v[242:245], v[206:209], v[58:61]
	v_mfma_f32_16x16x32_bf16 v[54:57], v[246:249], v[206:209], v[54:57]
	v_mfma_f32_16x16x32_bf16 v[50:53], v[222:225], v[206:209], v[50:53]
	v_add_u32_e32 v235, s7, v235
	s_barrier
	s_mov_b32 s38, s6
	s_mov_b32 s6, s7
	s_mov_b32 s7, s35
	s_mov_b32 s35, s38
	s_nop 7

; __device__ __forceinline__ int otid() { int t = threadIdx.x; asm volatile("" : "+v"(t)); return t; }
; template <int MODE>
; __device__ void gemm_tile2(const u16* __restrict__ X, int lda, const u16* __restrict__ W, int ldb, int K,
;                            int m0, int n0, u16* __restrict__ outb, int vbase,
;                            const float* resid, float* outf, unsigned char* smem) {
;   u16* sbase = (u16*)smem;
;   const int tid = otid(), lane = tid & 63, l15 = lane & 15, quad = lane >> 4;
;   const int wave = tid >> 6;
;   const int wx = wave >> 1, ww = wave & 1;
;   f32x4 acc[8][4];
; #pragma unroll
;   for (int i = 0; i < 8; ++i)
; #pragma unroll
;     for (int j = 0; j < 4; ++j) acc[i][j] = f32x4{0.f, 0.f, 0.f, 0.f};
;   u32x4 rx[2][4], rw[2][2];
;   const int lrow = tid >> 2, lkc = (tid & 3) * 8;
;   const int lsw = ((tid & 3) ^ ((0 - (lrow >> 2)) & 3)) * 8;
;   const int fsw = (quad ^ ((0 - (l15 >> 2)) & 3)) * 8;
;   const auto rsX = __builtin_amdgcn_make_buffer_rsrc((void*)(X + (size_t)m0 * lda), (short)0, 0x7fffffff, 0x00020000);
;   const auto rsW = __builtin_amdgcn_make_buffer_rsrc((void*)(W + (size_t)n0 * ldb), (short)0, 0x7fffffff, 0x00020000);
;   const int vox = (lrow * lda + lkc) * 2, vow = (lrow * ldb + lkc) * 2;
;   const int nk = K / 32;
;     ...
;   G2_GLOAD(0, 0);
;   G2_GLOAD(1, 1);
;   __syncthreads();
;   G2_LSTORE(0, 0);
;   G2_GLOAD(0, 2);
;   __syncthreads();
;   for (int kt2 = 0; kt2 < nk; kt2 += 2) {
; #pragma unroll
;     for (int h = 0; h < 2; ++h) {
;       const int kt = kt2 + h;
;       const u16* st = sbase + h * G2STAGE;
;       bf16x8 fw[4], fx[4];
; #pragma unroll
;       for (int j = 0; j < 4; ++j) fw[j] = *(const bf16x8*)(st + 256 * G2S + (ww * 64 + j * 16 + l15) * G2S + fsw);
; #pragma unroll
;       for (int i = 0; i < 4; ++i) fx[i] = *(const bf16x8*)(st + (wx * 128 + i * 16 + l15) * G2S + fsw);
;       __builtin_amdgcn_sched_barrier(0);
.LBB0_321:
	v_mov_b32_e32 v0, v210
	s_lshl_b32 s1, s31, 18
	s_lshl_b32 s6, s18, 19
	s_add_u32 s24, s36, s6
	s_addc_u32 s6, s37, 0
	s_and_b32 s25, s6, 0xffff
	s_add_u32 s40, s8, s1
	s_addc_u32 s1, s9, 0
	s_and_b32 s41, s1, 0xffff
	s_mov_b32 s42, s26
	s_mov_b32 s43, s27
	v_lshlrev_b32_e32 v230, 4, v0
	v_lshrrev_b32_e32 v231, 4, v0
	v_and_b32_e32 v232, 15, v0
	v_bfe_u32 v234, v0, 6, 1
	v_lshrrev_b32_e32 v2, 2, v0
	v_lshrrev_b32_e32 v3, 4, v0
	v_sub_u32_e32 v4, 0, v3
	v_xor_b32_e32 v4, v0, v4
	v_lshlrev_b32_e32 v4, 4, v4
	v_and_b32_e32 v4, 48, v4
	v_lshl_or_b32 v235, v2, 6, v4
	v_lshlrev_b32_e32 v4, 4, v0
	v_and_b32_e32 v4, 48, v4
	v_lshl_or_b32 v233, v2, 11, v4
	v_sub_u32_e32 v4, 0, v2
	v_xor_b32_e32 v4, v3, v4
	v_lshlrev_b32_e32 v4, 4, v4
	v_and_b32_e32 v4, 48, v4
	v_lshlrev_b32_e32 v5, 6, v0
	v_and_b32_e32 v6, 0x3c0, v5
	v_bfe_u32 v7, v0, 6, 1
	v_lshl_or_b32 v7, v7, 12, v4
	v_add_u32_e32 v236, v7, v6
	v_and_b32_e32 v5, 0xffffe3c0, v5
	v_add_u32_e32 v218, v4, v5
	v_add_u32_e32 v219, 0x6000, v218
	buffer_load_dwordx4 v[2:5], v233, s[24:27], 0 offen
	buffer_load_dwordx4 v[6:9], v233, s[24:27], s27 offen
	buffer_load_dwordx4 v[10:13], v233, s[24:27], s77 offen
	buffer_load_dwordx4 v[14:17], v233, s[24:27], s78 offen
	buffer_load_dwordx4 v[18:21], v233, s[40:43], 0 offen
	buffer_load_dwordx4 v[22:25], v233, s[40:43], s27 offen
	v_add_u32_e32 v233, 64, v233
	buffer_load_dwordx4 v[26:29], v233, s[24:27], 0 offen
	buffer_load_dwordx4 v[30:33], v233, s[24:27], s27 offen
	buffer_load_dwordx4 v[34:37], v233, s[24:27], s77 offen
	buffer_load_dwordx4 v[38:41], v233, s[24:27], s78 offen
	buffer_load_dwordx4 v[42:45], v233, s[40:43], 0 offen
	buffer_load_dwordx4 v[46:49], v233, s[40:43], s27 offen
	v_add_u32_e32 v233, 64, v233
	v_mov_b32_e32 v50, 0
	v_mov_b32_e32 v51, 0
	v_mov_b32_e32 v52, 0
	v_mov_b32_e32 v53, 0
	v_mov_b32_e32 v54, 0
	v_mov_b32_e32 v55, 0
	v_mov_b32_e32 v56, 0
	v_mov_b32_e32 v57, 0
	v_mov_b32_e32 v58, 0
	v_mov_b32_e32 v59, 0
	v_mov_b32_e32 v60, 0
	v_mov_b32_e32 v61, 0
	v_mov_b32_e32 v62, 0
	v_mov_b32_e32 v63, 0
	v_mov_b32_e32 v64, 0
	v_mov_b32_e32 v65, 0
	v_mov_b32_e32 v66, 0
	v_mov_b32_e32 v67, 0
	v_mov_b32_e32 v68, 0
	v_mov_b32_e32 v69, 0
	v_mov_b32_e32 v70, 0
	v_mov_b32_e32 v71, 0
	v_mov_b32_e32 v72, 0
	v_mov_b32_e32 v73, 0
	v_mov_b32_e32 v74, 0
	v_mov_b32_e32 v75, 0
	v_mov_b32_e32 v76, 0
	v_mov_b32_e32 v77, 0
	v_mov_b32_e32 v78, 0
	v_mov_b32_e32 v79, 0
	v_mov_b32_e32 v80, 0
	v_mov_b32_e32 v81, 0
	v_mov_b32_e32 v82, 0
	v_mov_b32_e32 v83, 0
	v_mov_b32_e32 v84, 0
	v_mov_b32_e32 v85, 0
	v_mov_b32_e32 v86, 0
	v_mov_b32_e32 v87, 0
	v_mov_b32_e32 v88, 0
	v_mov_b32_e32 v89, 0
	v_mov_b32_e32 v90, 0
	v_mov_b32_e32 v91, 0
	v_mov_b32_e32 v92, 0
	v_mov_b32_e32 v93, 0
	v_mov_b32_e32 v94, 0
	v_mov_b32_e32 v95, 0
	v_mov_b32_e32 v96, 0
	v_mov_b32_e32 v97, 0
	v_mov_b32_e32 v98, 0
	v_mov_b32_e32 v99, 0
	v_mov_b32_e32 v100, 0
	v_mov_b32_e32 v101, 0
	v_mov_b32_e32 v102, 0
	v_mov_b32_e32 v103, 0
	v_mov_b32_e32 v104, 0
	v_mov_b32_e32 v105, 0
	v_mov_b32_e32 v106, 0
	v_mov_b32_e32 v107, 0
	v_mov_b32_e32 v108, 0
	v_mov_b32_e32 v109, 0
	v_mov_b32_e32 v110, 0
	v_mov_b32_e32 v111, 0
	v_mov_b32_e32 v112, 0
	v_mov_b32_e32 v113, 0
	v_mov_b32_e32 v114, 0
	v_mov_b32_e32 v115, 0
	v_mov_b32_e32 v116, 0
	v_mov_b32_e32 v117, 0
	v_mov_b32_e32 v118, 0
	v_mov_b32_e32 v119, 0
	v_mov_b32_e32 v120, 0
	v_mov_b32_e32 v121, 0
	v_mov_b32_e32 v122, 0
	v_mov_b32_e32 v123, 0
	v_mov_b32_e32 v124, 0
	v_mov_b32_e32 v125, 0
	v_mov_b32_e32 v126, 0
	v_mov_b32_e32 v127, 0
	v_mov_b32_e32 v128, 0
	v_mov_b32_e32 v129, 0
	v_mov_b32_e32 v130, 0
	v_mov_b32_e32 v131, 0
	v_mov_b32_e32 v132, 0
	v_mov_b32_e32 v133, 0
	v_mov_b32_e32 v134, 0
	v_mov_b32_e32 v135, 0
	v_mov_b32_e32 v136, 0
	v_mov_b32_e32 v137, 0
	v_mov_b32_e32 v138, 0
	v_mov_b32_e32 v139, 0
	v_mov_b32_e32 v140, 0
	v_mov_b32_e32 v141, 0
	v_mov_b32_e32 v142, 0
	v_mov_b32_e32 v143, 0
	v_mov_b32_e32 v144, 0
	v_mov_b32_e32 v145, 0
	v_mov_b32_e32 v146, 0
	v_mov_b32_e32 v147, 0
	v_mov_b32_e32 v148, 0
	v_mov_b32_e32 v149, 0
	v_mov_b32_e32 v150, 0
	v_mov_b32_e32 v151, 0
	v_mov_b32_e32 v152, 0
	v_mov_b32_e32 v153, 0
	v_mov_b32_e32 v154, 0
	v_mov_b32_e32 v155, 0
	v_mov_b32_e32 v156, 0
	v_mov_b32_e32 v157, 0
	v_mov_b32_e32 v158, 0
	v_mov_b32_e32 v159, 0
	v_mov_b32_e32 v160, 0
	v_mov_b32_e32 v161, 0
	v_mov_b32_e32 v162, 0
	v_mov_b32_e32 v163, 0
	v_mov_b32_e32 v164, 0
	v_mov_b32_e32 v165, 0
	v_mov_b32_e32 v166, 0
	v_mov_b32_e32 v167, 0
	v_mov_b32_e32 v168, 0
	v_mov_b32_e32 v169, 0
	v_mov_b32_e32 v170, 0
	v_mov_b32_e32 v171, 0
	v_mov_b32_e32 v172, 0
	v_mov_b32_e32 v173, 0
	v_mov_b32_e32 v174, 0
	v_mov_b32_e32 v175, 0
	v_mov_b32_e32 v176, 0
	v_mov_b32_e32 v177, 0
	s_mov_b32 s1, 0x6000
	s_mov_b32 s6, 0x6000
	s_mov_b32 s7, 0xffff4000
	s_mov_b32 s0, 0
	s_barrier
	s_waitcnt vmcnt(6)
	ds_write_b128 v235, v[2:5]
	ds_write_b128 v235, v[6:9] offset:4096
	ds_write_b128 v235, v[10:13] offset:8192
	ds_write_b128 v235, v[14:17] offset:12288
	ds_write_b128 v235, v[18:21] offset:16384
	ds_write_b128 v235, v[22:25] offset:20480
	buffer_load_dwordx4 v[2:5], v233, s[24:27], 0 offen
	buffer_load_dwordx4 v[6:9], v233, s[24:27], s27 offen
	buffer_load_dwordx4 v[10:13], v233, s[24:27], s77 offen
	buffer_load_dwordx4 v[14:17], v233, s[24:27], s78 offen
	buffer_load_dwordx4 v[18:21], v233, s[40:43], 0 offen
	buffer_load_dwordx4 v[22:25], v233, s[40:43], s27 offen
	v_add_u32_e32 v233, 64, v233
	v_add_u32_e32 v235, 0x6000, v235
	s_waitcnt vmcnt(6)
	ds_write_b128 v235, v[26:29]
	ds_write_b128 v235, v[30:33] offset:4096
	ds_write_b128 v235, v[34:37] offset:8192
	ds_write_b128 v235, v[38:41] offset:12288
	ds_write_b128 v235, v[42:45] offset:16384
	ds_write_b128 v235, v[46:49] offset:20480
	buffer_load_dwordx4 v[26:29], v233, s[24:27], 0 offen
	buffer_load_dwordx4 v[30:33], v233, s[24:27], s27 offen
	buffer_load_dwordx4 v[34:37], v233, s[24:27], s77 offen
	buffer_load_dwordx4 v[38:41], v233, s[24:27], s78 offen
	buffer_load_dwordx4 v[42:45], v233, s[40:43], 0 offen
	buffer_load_dwordx4 v[46:49], v233, s[40:43], s27 offen
	v_add_u32_e32 v233, 64, v233
	v_add_u32_e32 v235, 0x6000, v235
	s_waitcnt lgkmcnt(0)
	s_barrier
	ds_read_b128 v[178:181], v236 offset:16384
	ds_read_b128 v[182:185], v236 offset:17408
	ds_read_b128 v[186:189], v236 offset:18432
	ds_read_b128 v[190:193], v236 offset:19456
	v_add_u32_e32 v236, 0x6000, v236
	ds_read_b128 v[194:197], v218
	ds_read_b128 v[198:201], v218 offset:1024
	ds_read_b128 v[202:205], v218 offset:2048
	ds_read_b128 v[206:209], v218 offset:3072
	s_waitcnt lgkmcnt(0)
; template <int MODE>
; __device__ void gemm_tile2(const u16* __restrict__ X, int lda, const u16* __restrict__ W, int ldb, int K,
;                            int m0, int n0, u16* __restrict__ outb, int vbase,
;                            const float* resid, float* outf, unsigned char* smem) {
;     ...
;   G2_GLOAD(0, 0);
;   G2_GLOAD(1, 1);
;   __syncthreads();
;   G2_LSTORE(0, 0);
;   G2_GLOAD(0, 2);
;   __syncthreads();
;   for (int kt2 = 0; kt2 < nk; kt2 += 2) {
; #pragma unroll
;     for (int h = 0; h < 2; ++h) {
;       const int kt = kt2 + h;
;       const u16* st = sbase + h * G2STAGE;
;       bf16x8 fw[4], fx[4];
; #pragma unroll
;       for (int j = 0; j < 4; ++j) fw[j] = *(const bf16x8*)(st + 256 * G2S + (ww * 64 + j * 16 + l15) * G2S + fsw);
; #pragma unroll
;       for (int i = 0; i < 4; ++i) fx[i] = *(const bf16x8*)(st + (wx * 128 + i * 16 + l15) * G2S + fsw);
;       __builtin_amdgcn_sched_barrier(0);
;       __builtin_amdgcn_s_setprio(1);
; #pragma unroll
;       for (int i = 0; i < 4; ++i) {
; #pragma unroll
;         for (int j = 0; j < 4; ++j) {
;           if (MODE == 1) acc[i][j] = mfma16(fx[i], fw[j], acc[i][j]);
;           else acc[i][j] = mfma16(fw[j], fx[i], acc[i][j]);
;         }
;       }
;       __builtin_amdgcn_s_setprio(0);
;       __builtin_amdgcn_sched_barrier(0);
; #pragma unroll
;       for (int i = 0; i < 4; ++i) fx[i] = *(const bf16x8*)(st + (wx * 128 + (i + 4) * 16 + l15) * G2S + fsw);
;       __builtin_amdgcn_sched_barrier(0);
;       if (kt + 1 < nk) G2_LSTORE(1 - h, 1 - h);
;       if (kt + 3 < nk) G2_GLOAD(1 - h, kt + 3);
;       __builtin_amdgcn_sched_barrier(0);
;       __builtin_amdgcn_s_setprio(1);
; #pragma unroll
;       for (int i = 0; i < 4; ++i) {
; #pragma unroll
;         for (int j = 0; j < 4; ++j) {
;           if (MODE == 1) acc[i + 4][j] = mfma16(fx[i], fw[j], acc[i + 4][j]);
;           else acc[i + 4][j] = mfma16(fw[j], fx[i], acc[i + 4][j]);
;         }
;       }
;       __builtin_amdgcn_s_setprio(0);
;       __syncthreads();
;     }
.Lh1_loop:
	v_mfma_f32_16x16x32_bf16 v[174:177], v[194:197], v[178:181], v[174:177]
	v_mfma_f32_16x16x32_bf16 v[170:173], v[194:197], v[182:185], v[170:173]
	v_mfma_f32_16x16x32_bf16 v[166:169], v[194:197], v[186:189], v[166:169]
	v_mfma_f32_16x16x32_bf16 v[162:165], v[194:197], v[190:193], v[162:165]
	ds_read_b128 v[194:197], v218 offset:4096
	ds_read_b128 v[238:241], v236 offset:16384
	v_mfma_f32_16x16x32_bf16 v[158:161], v[198:201], v[178:181], v[158:161]
	v_mfma_f32_16x16x32_bf16 v[154:157], v[198:201], v[182:185], v[154:157]
	v_mfma_f32_16x16x32_bf16 v[150:153], v[198:201], v[186:189], v[150:153]
	v_mfma_f32_16x16x32_bf16 v[146:149], v[198:201], v[190:193], v[146:149]
	ds_read_b128 v[198:201], v218 offset:5120
	ds_read_b128 v[242:245], v236 offset:17408
	v_mfma_f32_16x16x32_bf16 v[142:145], v[202:205], v[178:181], v[142:145]
	v_mfma_f32_16x16x32_bf16 v[138:141], v[202:205], v[182:185], v[138:141]
	v_mfma_f32_16x16x32_bf16 v[134:137], v[202:205], v[186:189], v[134:137]
	v_mfma_f32_16x16x32_bf16 v[130:133], v[202:205], v[190:193], v[130:133]
	ds_read_b128 v[202:205], v218 offset:6144
	ds_read_b128 v[246:249], v236 offset:18432
	s_waitcnt lgkmcnt(6)
	v_mfma_f32_16x16x32_bf16 v[126:129], v[206:209], v[178:181], v[126:129]
	v_mfma_f32_16x16x32_bf16 v[122:125], v[206:209], v[182:185], v[122:125]
	v_mfma_f32_16x16x32_bf16 v[118:121], v[206:209], v[186:189], v[118:121]
	v_mfma_f32_16x16x32_bf16 v[114:117], v[206:209], v[190:193], v[114:117]
	ds_read_b128 v[206:209], v218 offset:7168
	ds_read_b128 v[222:225], v236 offset:19456
	s_add_i32 s35, s1, s6
	v_add_u32_e32 v218, s35, v218
	s_waitcnt lgkmcnt(7)
	v_mfma_f32_16x16x32_bf16 v[110:113], v[194:197], v[178:181], v[110:113]
	v_mfma_f32_16x16x32_bf16 v[106:109], v[194:197], v[182:185], v[106:109]
	v_mfma_f32_16x16x32_bf16 v[102:105], v[194:197], v[186:189], v[102:105]
	v_mfma_f32_16x16x32_bf16 v[98:101], v[194:197], v[190:193], v[98:101]
	ds_read_b128 v[194:197], v219
	s_waitcnt vmcnt(6)
	ds_write_b128 v235, v[2:5]
	ds_write_b128 v235, v[6:9] offset:4096
	s_waitcnt lgkmcnt(8)
	v_mfma_f32_16x16x32_bf16 v[94:97], v[198:201], v[178:181], v[94:97]
	v_mfma_f32_16x16x32_bf16 v[90:93], v[198:201], v[182:185], v[90:93]
	v_mfma_f32_16x16x32_bf16 v[86:89], v[198:201], v[186:189], v[86:89]
	v_mfma_f32_16x16x32_bf16 v[82:85], v[198:201], v[190:193], v[82:85]
	ds_read_b128 v[198:201], v219 offset:1024
	ds_write_b128 v235, v[10:13] offset:8192
	ds_write_b128 v235, v[14:17] offset:12288
	s_waitcnt lgkmcnt(9)
	v_mfma_f32_16x16x32_bf16 v[78:81], v[202:205], v[178:181], v[78:81]
	v_mfma_f32_16x16x32_bf16 v[74:77], v[202:205], v[182:185], v[74:77]
	v_mfma_f32_16x16x32_bf16 v[70:73], v[202:205], v[186:189], v[70:73]
	v_mfma_f32_16x16x32_bf16 v[66:69], v[202:205], v[190:193], v[66:69]
	ds_read_b128 v[202:205], v219 offset:2048
	ds_write_b128 v235, v[18:21] offset:16384
	ds_write_b128 v235, v[22:25] offset:20480
	v_add_u32_e32 v235, s7, v235
	s_waitcnt lgkmcnt(10)
	v_mfma_f32_16x16x32_bf16 v[62:65], v[206:209], v[178:181], v[62:65]
	v_mfma_f32_16x16x32_bf16 v[58:61], v[206:209], v[182:185], v[58:61]
	v_mfma_f32_16x16x32_bf16 v[54:57], v[206:209], v[186:189], v[54:57]
	v_mfma_f32_16x16x32_bf16 v[50:53], v[206:209], v[190:193], v[50:53]
	ds_read_b128 v[206:209], v219 offset:3072
	v_add_u32_e32 v236, s6, v236
	buffer_load_dwordx4 v[2:5], v233, s[24:27], 0 offen
	buffer_load_dwordx4 v[6:9], v233, s[24:27], s27 offen
	buffer_load_dwordx4 v[10:13], v233, s[24:27], s77 offen
	buffer_load_dwordx4 v[14:17], v233, s[24:27], s78 offen
	buffer_load_dwordx4 v[18:21], v233, s[40:43], 0 offen
	buffer_load_dwordx4 v[22:25], v233, s[40:43], s27 offen
	v_add_u32_e32 v233, 64, v233
	s_waitcnt lgkmcnt(1)
	s_barrier
	s_mov_b32 s35, s1
	s_mov_b32 s1, s6
	s_mov_b32 s6, s7
	s_mov_b32 s7, s35
	v_mfma_f32_16x16x32_bf16 v[174:177], v[194:197], v[238:241], v[174:177]
	v_mfma_f32_16x16x32_bf16 v[170:173], v[194:197], v[242:245], v[170:173]
	v_mfma_f32_16x16x32_bf16 v[166:169], v[194:197], v[246:249], v[166:169]
	v_mfma_f32_16x16x32_bf16 v[162:165], v[194:197], v[222:225], v[162:165]
	ds_read_b128 v[194:197], v219 offset:4096
	ds_read_b128 v[178:181], v236 offset:16384
	v_mfma_f32_16x16x32_bf16 v[158:161], v[198:201], v[238:241], v[158:161]
	v_mfma_f32_16x16x32_bf16 v[154:157], v[198:201], v[242:245], v[154:157]
	v_mfma_f32_16x16x32_bf16 v[150:153], v[198:201], v[246:249], v[150:153]
	v_mfma_f32_16x16x32_bf16 v[146:149], v[198:201], v[222:225], v[146:149]
	ds_read_b128 v[198:201], v219 offset:5120
	ds_read_b128 v[182:185], v236 offset:17408
	v_mfma_f32_16x16x32_bf16 v[142:145], v[202:205], v[238:241], v[142:145]
	v_mfma_f32_16x16x32_bf16 v[138:141], v[202:205], v[242:245], v[138:141]
	v_mfma_f32_16x16x32_bf16 v[134:137], v[202:205], v[246:249], v[134:137]
	v_mfma_f32_16x16x32_bf16 v[130:133], v[202:205], v[222:225], v[130:133]
	ds_read_b128 v[202:205], v219 offset:6144
	ds_read_b128 v[186:189], v236 offset:18432
	s_waitcnt lgkmcnt(6)
	v_mfma_f32_16x16x32_bf16 v[126:129], v[206:209], v[238:241], v[126:129]
	v_mfma_f32_16x16x32_bf16 v[122:125], v[206:209], v[242:245], v[122:125]
	v_mfma_f32_16x16x32_bf16 v[118:121], v[206:209], v[246:249], v[118:121]
	v_mfma_f32_16x16x32_bf16 v[114:117], v[206:209], v[222:225], v[114:117]
	ds_read_b128 v[206:209], v219 offset:7168
	ds_read_b128 v[190:193], v236 offset:19456
	s_add_i32 s35, s1, s6
	v_add_u32_e32 v219, s35, v219
	s_waitcnt lgkmcnt(7)
	v_mfma_f32_16x16x32_bf16 v[110:113], v[194:197], v[238:241], v[110:113]
	v_mfma_f32_16x16x32_bf16 v[106:109], v[194:197], v[242:245], v[106:109]
	v_mfma_f32_16x16x32_bf16 v[102:105], v[194:197], v[246:249], v[102:105]
	v_mfma_f32_16x16x32_bf16 v[98:101], v[194:197], v[222:225], v[98:101]
	ds_read_b128 v[194:197], v218
	s_waitcnt vmcnt(6)
; template <int MODE>
; __device__ void gemm_tile2(const u16* __restrict__ X, int lda, const u16* __restrict__ W, int ldb, int K,
;                            int m0, int n0, u16* __restrict__ outb, int vbase,
;                            const float* resid, float* outf, unsigned char* smem) {
;     ...
;   G2_GLOAD(0, 0);
;   G2_GLOAD(1, 1);
;   __syncthreads();
;   G2_LSTORE(0, 0);
;   G2_GLOAD(0, 2);
;   __syncthreads();
;   for (int kt2 = 0; kt2 < nk; kt2 += 2) {
; #pragma unroll
;     for (int h = 0; h < 2; ++h) {
;       const int kt = kt2 + h;
;       const u16* st = sbase + h * G2STAGE;
;       bf16x8 fw[4], fx[4];
; #pragma unroll
;       for (int j = 0; j < 4; ++j) fw[j] = *(const bf16x8*)(st + 256 * G2S + (ww * 64 + j * 16 + l15) * G2S + fsw);
; #pragma unroll
;       for (int i = 0; i < 4; ++i) fx[i] = *(const bf16x8*)(st + (wx * 128 + i * 16 + l15) * G2S + fsw);
;       __builtin_amdgcn_sched_barrier(0);
;       __builtin_amdgcn_s_setprio(1);
; #pragma unroll
;       for (int i = 0; i < 4; ++i) {
; #pragma unroll
;         for (int j = 0; j < 4; ++j) {
;           if (MODE == 1) acc[i][j] = mfma16(fx[i], fw[j], acc[i][j]);
;           else acc[i][j] = mfma16(fw[j], fx[i], acc[i][j]);
;         }
;       }
;       __builtin_amdgcn_s_setprio(0);
;       __builtin_amdgcn_sched_barrier(0);
; #pragma unroll
;       for (int i = 0; i < 4; ++i) fx[i] = *(const bf16x8*)(st + (wx * 128 + (i + 4) * 16 + l15) * G2S + fsw);
;       __builtin_amdgcn_sched_barrier(0);
;       if (kt + 1 < nk) G2_LSTORE(1 - h, 1 - h);
;       if (kt + 3 < nk) G2_GLOAD(1 - h, kt + 3);
;       __builtin_amdgcn_sched_barrier(0);
;       __builtin_amdgcn_s_setprio(1);
; #pragma unroll
;       for (int i = 0; i < 4; ++i) {
; #pragma unroll
;         for (int j = 0; j < 4; ++j) {
;           if (MODE == 1) acc[i + 4][j] = mfma16(fx[i], fw[j], acc[i + 4][j]);
;           else acc[i + 4][j] = mfma16(fw[j], fx[i], acc[i + 4][j]);
;         }
;       }
;       __builtin_amdgcn_s_setprio(0);
;       __syncthreads();
;     }
	ds_write_b128 v235, v[26:29]
	ds_write_b128 v235, v[30:33] offset:4096
	s_waitcnt lgkmcnt(8)
	v_mfma_f32_16x16x32_bf16 v[94:97], v[198:201], v[238:241], v[94:97]
	v_mfma_f32_16x16x32_bf16 v[90:93], v[198:201], v[242:245], v[90:93]
	v_mfma_f32_16x16x32_bf16 v[86:89], v[198:201], v[246:249], v[86:89]
	v_mfma_f32_16x16x32_bf16 v[82:85], v[198:201], v[222:225], v[82:85]
	ds_read_b128 v[198:201], v218 offset:1024
	ds_write_b128 v235, v[34:37] offset:8192
	ds_write_b128 v235, v[38:41] offset:12288
	s_waitcnt lgkmcnt(9)
	v_mfma_f32_16x16x32_bf16 v[78:81], v[202:205], v[238:241], v[78:81]
	v_mfma_f32_16x16x32_bf16 v[74:77], v[202:205], v[242:245], v[74:77]
	v_mfma_f32_16x16x32_bf16 v[70:73], v[202:205], v[246:249], v[70:73]
	v_mfma_f32_16x16x32_bf16 v[66:69], v[202:205], v[222:225], v[66:69]
	ds_read_b128 v[202:205], v218 offset:2048
	ds_write_b128 v235, v[42:45] offset:16384
	ds_write_b128 v235, v[46:49] offset:20480
	v_add_u32_e32 v235, s7, v235
	s_waitcnt lgkmcnt(10)
	v_mfma_f32_16x16x32_bf16 v[62:65], v[206:209], v[238:241], v[62:65]
	v_mfma_f32_16x16x32_bf16 v[58:61], v[206:209], v[242:245], v[58:61]
	v_mfma_f32_16x16x32_bf16 v[54:57], v[206:209], v[246:249], v[54:57]
	v_mfma_f32_16x16x32_bf16 v[50:53], v[206:209], v[222:225], v[50:53]
	ds_read_b128 v[206:209], v218 offset:3072
	v_add_u32_e32 v236, s6, v236
	buffer_load_dwordx4 v[26:29], v233, s[24:27], 0 offen
	buffer_load_dwordx4 v[30:33], v233, s[24:27], s27 offen
	buffer_load_dwordx4 v[34:37], v233, s[24:27], s77 offen
	buffer_load_dwordx4 v[38:41], v233, s[24:27], s78 offen
	buffer_load_dwordx4 v[42:45], v233, s[40:43], 0 offen
	buffer_load_dwordx4 v[46:49], v233, s[40:43], s27 offen
	v_add_u32_e32 v233, 64, v233
	s_waitcnt lgkmcnt(1)
	s_barrier
	s_mov_b32 s35, s1
	s_mov_b32 s1, s6
	s_mov_b32 s6, s7
	s_mov_b32 s7, s35
	s_add_u32 s0, s0, 2
	s_cmp_lt_u32 s0, 28
	s_cbranch_scc1 .Lh1_loop
	v_mfma_f32_16x16x32_bf16 v[174:177], v[194:197], v[178:181], v[174:177]
	v_mfma_f32_16x16x32_bf16 v[170:173], v[194:197], v[182:185], v[170:173]
	v_mfma_f32_16x16x32_bf16 v[166:169], v[194:197], v[186:189], v[166:169]
	v_mfma_f32_16x16x32_bf16 v[162:165], v[194:197], v[190:193], v[162:165]
	ds_read_b128 v[194:197], v218 offset:4096
	ds_read_b128 v[238:241], v236 offset:16384
	v_mfma_f32_16x16x32_bf16 v[158:161], v[198:201], v[178:181], v[158:161]
	v_mfma_f32_16x16x32_bf16 v[154:157], v[198:201], v[182:185], v[154:157]
	v_mfma_f32_16x16x32_bf16 v[150:153], v[198:201], v[186:189], v[150:153]
	v_mfma_f32_16x16x32_bf16 v[146:149], v[198:201], v[190:193], v[146:149]
	ds_read_b128 v[198:201], v218 offset:5120
	ds_read_b128 v[242:245], v236 offset:17408
	v_mfma_f32_16x16x32_bf16 v[142:145], v[202:205], v[178:181], v[142:145]
	v_mfma_f32_16x16x32_bf16 v[138:141], v[202:205], v[182:185], v[138:141]
	v_mfma_f32_16x16x32_bf16 v[134:137], v[202:205], v[186:189], v[134:137]
	v_mfma_f32_16x16x32_bf16 v[130:133], v[202:205], v[190:193], v[130:133]
	ds_read_b128 v[202:205], v218 offset:6144
	ds_read_b128 v[246:249], v236 offset:18432
	s_waitcnt lgkmcnt(6)
	v_mfma_f32_16x16x32_bf16 v[126:129], v[206:209], v[178:181], v[126:129]
	v_mfma_f32_16x16x32_bf16 v[122:125], v[206:209], v[182:185], v[122:125]
	v_mfma_f32_16x16x32_bf16 v[118:121], v[206:209], v[186:189], v[118:121]
	v_mfma_f32_16x16x32_bf16 v[114:117], v[206:209], v[190:193], v[114:117]
	ds_read_b128 v[206:209], v218 offset:7168
	ds_read_b128 v[222:225], v236 offset:19456
	s_add_i32 s35, s1, s6
	v_add_u32_e32 v218, s35, v218
	s_waitcnt lgkmcnt(7)
	v_mfma_f32_16x16x32_bf16 v[110:113], v[194:197], v[178:181], v[110:113]
	v_mfma_f32_16x16x32_bf16 v[106:109], v[194:197], v[182:185], v[106:109]
	v_mfma_f32_16x16x32_bf16 v[102:105], v[194:197], v[186:189], v[102:105]
	v_mfma_f32_16x16x32_bf16 v[98:101], v[194:197], v[190:193], v[98:101]
	ds_read_b128 v[194:197], v219
	s_waitcnt vmcnt(6)
	ds_write_b128 v235, v[2:5]
	ds_write_b128 v235, v[6:9] offset:4096
	s_waitcnt lgkmcnt(8)
	v_mfma_f32_16x16x32_bf16 v[94:97], v[198:201], v[178:181], v[94:97]
	v_mfma_f32_16x16x32_bf16 v[90:93], v[198:201], v[182:185], v[90:93]
	v_mfma_f32_16x16x32_bf16 v[86:89], v[198:201], v[186:189], v[86:89]
	v_mfma_f32_16x16x32_bf16 v[82:85], v[198:201], v[190:193], v[82:85]
	ds_read_b128 v[198:201], v219 offset:1024
	ds_write_b128 v235, v[10:13] offset:8192
	ds_write_b128 v235, v[14:17] offset:12288
	s_waitcnt lgkmcnt(9)
	v_mfma_f32_16x16x32_bf16 v[78:81], v[202:205], v[178:181], v[78:81]
	v_mfma_f32_16x16x32_bf16 v[74:77], v[202:205], v[182:185], v[74:77]
	v_mfma_f32_16x16x32_bf16 v[70:73], v[202:205], v[186:189], v[70:73]
	v_mfma_f32_16x16x32_bf16 v[66:69], v[202:205], v[190:193], v[66:69]
	ds_read_b128 v[202:205], v219 offset:2048
	ds_write_b128 v235, v[18:21] offset:16384
	ds_write_b128 v235, v[22:25] offset:20480
	v_add_u32_e32 v235, s7, v235
	s_waitcnt lgkmcnt(10)
	v_mfma_f32_16x16x32_bf16 v[62:65], v[206:209], v[178:181], v[62:65]
	v_mfma_f32_16x16x32_bf16 v[58:61], v[206:209], v[182:185], v[58:61]
	v_mfma_f32_16x16x32_bf16 v[54:57], v[206:209], v[186:189], v[54:57]
	v_mfma_f32_16x16x32_bf16 v[50:53], v[206:209], v[190:193], v[50:53]
	ds_read_b128 v[206:209], v219 offset:3072
	v_add_u32_e32 v236, s6, v236
	s_waitcnt lgkmcnt(1)
	s_barrier
; template <int MODE>
; __device__ void gemm_tile2(const u16* __restrict__ X, int lda, const u16* __restrict__ W, int ldb, int K,
;                            int m0, int n0, u16* __restrict__ outb, int vbase,
;                            const float* resid, float* outf, unsigned char* smem) {
;     ...
;   G2_GLOAD(0, 0);
;   G2_GLOAD(1, 1);
;   __syncthreads();
;   G2_LSTORE(0, 0);
;   G2_GLOAD(0, 2);
;   __syncthreads();
;   for (int kt2 = 0; kt2 < nk; kt2 += 2) {
; #pragma unroll
;     for (int h = 0; h < 2; ++h) {
;       const int kt = kt2 + h;
;       const u16* st = sbase + h * G2STAGE;
;       bf16x8 fw[4], fx[4];
; #pragma unroll
;       for (int j = 0; j < 4; ++j) fw[j] = *(const bf16x8*)(st + 256 * G2S + (ww * 64 + j * 16 + l15) * G2S + fsw);
; #pragma unroll
;       for (int i = 0; i < 4; ++i) fx[i] = *(const bf16x8*)(st + (wx * 128 + i * 16 + l15) * G2S + fsw);
;       __builtin_amdgcn_sched_barrier(0);
;       __builtin_amdgcn_s_setprio(1);
; #pragma unroll
;       for (int i = 0; i < 4; ++i) {
; #pragma unroll
;         for (int j = 0; j < 4; ++j) {
;           if (MODE == 1) acc[i][j] = mfma16(fx[i], fw[j], acc[i][j]);
;           else acc[i][j] = mfma16(fw[j], fx[i], acc[i][j]);
;         }
;       }
;       __builtin_amdgcn_s_setprio(0);
;       __builtin_amdgcn_sched_barrier(0);
; #pragma unroll
;       for (int i = 0; i < 4; ++i) fx[i] = *(const bf16x8*)(st + (wx * 128 + (i + 4) * 16 + l15) * G2S + fsw);
;       __builtin_amdgcn_sched_barrier(0);
;       if (kt + 1 < nk) G2_LSTORE(1 - h, 1 - h);
;       if (kt + 3 < nk) G2_GLOAD(1 - h, kt + 3);
;       __builtin_amdgcn_sched_barrier(0);
;       __builtin_amdgcn_s_setprio(1);
; #pragma unroll
;       for (int i = 0; i < 4; ++i) {
; #pragma unroll
;         for (int j = 0; j < 4; ++j) {
;           if (MODE == 1) acc[i + 4][j] = mfma16(fx[i], fw[j], acc[i + 4][j]);
;           else acc[i + 4][j] = mfma16(fw[j], fx[i], acc[i + 4][j]);
;         }
;       }
;       __builtin_amdgcn_s_setprio(0);
;       __syncthreads();
;     }
	s_mov_b32 s35, s1
	s_mov_b32 s1, s6
	s_mov_b32 s6, s7
	s_mov_b32 s7, s35
	v_mfma_f32_16x16x32_bf16 v[174:177], v[194:197], v[238:241], v[174:177]
	v_mfma_f32_16x16x32_bf16 v[170:173], v[194:197], v[242:245], v[170:173]
	v_mfma_f32_16x16x32_bf16 v[166:169], v[194:197], v[246:249], v[166:169]
	v_mfma_f32_16x16x32_bf16 v[162:165], v[194:197], v[222:225], v[162:165]
	ds_read_b128 v[194:197], v219 offset:4096
	ds_read_b128 v[178:181], v236 offset:16384
	v_mfma_f32_16x16x32_bf16 v[158:161], v[198:201], v[238:241], v[158:161]
	v_mfma_f32_16x16x32_bf16 v[154:157], v[198:201], v[242:245], v[154:157]
	v_mfma_f32_16x16x32_bf16 v[150:153], v[198:201], v[246:249], v[150:153]
	v_mfma_f32_16x16x32_bf16 v[146:149], v[198:201], v[222:225], v[146:149]
	ds_read_b128 v[198:201], v219 offset:5120
	ds_read_b128 v[182:185], v236 offset:17408
	v_mfma_f32_16x16x32_bf16 v[142:145], v[202:205], v[238:241], v[142:145]
	v_mfma_f32_16x16x32_bf16 v[138:141], v[202:205], v[242:245], v[138:141]
	v_mfma_f32_16x16x32_bf16 v[134:137], v[202:205], v[246:249], v[134:137]
	v_mfma_f32_16x16x32_bf16 v[130:133], v[202:205], v[222:225], v[130:133]
	ds_read_b128 v[202:205], v219 offset:6144
	ds_read_b128 v[186:189], v236 offset:18432
	s_waitcnt lgkmcnt(6)
	v_mfma_f32_16x16x32_bf16 v[126:129], v[206:209], v[238:241], v[126:129]
	v_mfma_f32_16x16x32_bf16 v[122:125], v[206:209], v[242:245], v[122:125]
	v_mfma_f32_16x16x32_bf16 v[118:121], v[206:209], v[246:249], v[118:121]
	v_mfma_f32_16x16x32_bf16 v[114:117], v[206:209], v[222:225], v[114:117]
	ds_read_b128 v[206:209], v219 offset:7168
	ds_read_b128 v[190:193], v236 offset:19456
	s_add_i32 s35, s1, s6
	v_add_u32_e32 v219, s35, v219
	s_waitcnt lgkmcnt(7)
	v_mfma_f32_16x16x32_bf16 v[110:113], v[194:197], v[238:241], v[110:113]
	v_mfma_f32_16x16x32_bf16 v[106:109], v[194:197], v[242:245], v[106:109]
	v_mfma_f32_16x16x32_bf16 v[102:105], v[194:197], v[246:249], v[102:105]
	v_mfma_f32_16x16x32_bf16 v[98:101], v[194:197], v[222:225], v[98:101]
	ds_read_b128 v[194:197], v218
	s_waitcnt vmcnt(0)
	ds_write_b128 v235, v[26:29]
	ds_write_b128 v235, v[30:33] offset:4096
	s_waitcnt lgkmcnt(8)
	v_mfma_f32_16x16x32_bf16 v[94:97], v[198:201], v[238:241], v[94:97]
	v_mfma_f32_16x16x32_bf16 v[90:93], v[198:201], v[242:245], v[90:93]
	v_mfma_f32_16x16x32_bf16 v[86:89], v[198:201], v[246:249], v[86:89]
	v_mfma_f32_16x16x32_bf16 v[82:85], v[198:201], v[222:225], v[82:85]
	ds_read_b128 v[198:201], v218 offset:1024
	ds_write_b128 v235, v[34:37] offset:8192
	ds_write_b128 v235, v[38:41] offset:12288
	s_waitcnt lgkmcnt(9)
	v_mfma_f32_16x16x32_bf16 v[78:81], v[202:205], v[238:241], v[78:81]
	v_mfma_f32_16x16x32_bf16 v[74:77], v[202:205], v[242:245], v[74:77]
	v_mfma_f32_16x16x32_bf16 v[70:73], v[202:205], v[246:249], v[70:73]
	v_mfma_f32_16x16x32_bf16 v[66:69], v[202:205], v[222:225], v[66:69]
	ds_read_b128 v[202:205], v218 offset:2048
	ds_write_b128 v235, v[42:45] offset:16384
	ds_write_b128 v235, v[46:49] offset:20480
	v_add_u32_e32 v235, s7, v235
	s_waitcnt lgkmcnt(10)
	v_mfma_f32_16x16x32_bf16 v[62:65], v[206:209], v[238:241], v[62:65]
	v_mfma_f32_16x16x32_bf16 v[58:61], v[206:209], v[242:245], v[58:61]
	v_mfma_f32_16x16x32_bf16 v[54:57], v[206:209], v[246:249], v[54:57]
	v_mfma_f32_16x16x32_bf16 v[50:53], v[206:209], v[222:225], v[50:53]
	ds_read_b128 v[206:209], v218 offset:3072
	v_add_u32_e32 v236, s6, v236
	s_waitcnt lgkmcnt(1)
	s_barrier
; template <int MODE>
; __device__ void gemm_tile2(const u16* __restrict__ X, int lda, const u16* __restrict__ W, int ldb, int K,
;                            int m0, int n0, u16* __restrict__ outb, int vbase,
;                            const float* resid, float* outf, unsigned char* smem) {
;     ...
;   G2_GLOAD(0, 0);
;   G2_GLOAD(1, 1);
;   __syncthreads();
;   G2_LSTORE(0, 0);
;   G2_GLOAD(0, 2);
;   __syncthreads();
;   for (int kt2 = 0; kt2 < nk; kt2 += 2) {
; #pragma unroll
;     for (int h = 0; h < 2; ++h) {
;       const int kt = kt2 + h;
;       const u16* st = sbase + h * G2STAGE;
;       bf16x8 fw[4], fx[4];
; #pragma unroll
;       for (int j = 0; j < 4; ++j) fw[j] = *(const bf16x8*)(st + 256 * G2S + (ww * 64 + j * 16 + l15) * G2S + fsw);
; #pragma unroll
;       for (int i = 0; i < 4; ++i) fx[i] = *(const bf16x8*)(st + (wx * 128 + i * 16 + l15) * G2S + fsw);
;       __builtin_amdgcn_sched_barrier(0);
;       __builtin_amdgcn_s_setprio(1);
; #pragma unroll
;       for (int i = 0; i < 4; ++i) {
; #pragma unroll
;         for (int j = 0; j < 4; ++j) {
;           if (MODE == 1) acc[i][j] = mfma16(fx[i], fw[j], acc[i][j]);
;           else acc[i][j] = mfma16(fw[j], fx[i], acc[i][j]);
;         }
;       }
;       __builtin_amdgcn_s_setprio(0);
;       __builtin_amdgcn_sched_barrier(0);
; #pragma unroll
;       for (int i = 0; i < 4; ++i) fx[i] = *(const bf16x8*)(st + (wx * 128 + (i + 4) * 16 + l15) * G2S + fsw);
;       __builtin_amdgcn_sched_barrier(0);
;       if (kt + 1 < nk) G2_LSTORE(1 - h, 1 - h);
;       if (kt + 3 < nk) G2_GLOAD(1 - h, kt + 3);
;       __builtin_amdgcn_sched_barrier(0);
;       __builtin_amdgcn_s_setprio(1);
; #pragma unroll
;       for (int i = 0; i < 4; ++i) {
; #pragma unroll
;         for (int j = 0; j < 4; ++j) {
;           if (MODE == 1) acc[i + 4][j] = mfma16(fx[i], fw[j], acc[i + 4][j]);
;           else acc[i + 4][j] = mfma16(fw[j], fx[i], acc[i + 4][j]);
;         }
;       }
;       __builtin_amdgcn_s_setprio(0);
;       __syncthreads();
;     }
	s_mov_b32 s35, s1
	s_mov_b32 s1, s6
	s_mov_b32 s6, s7
	s_mov_b32 s7, s35
	v_mfma_f32_16x16x32_bf16 v[174:177], v[194:197], v[178:181], v[174:177]
	v_mfma_f32_16x16x32_bf16 v[170:173], v[194:197], v[182:185], v[170:173]
	v_mfma_f32_16x16x32_bf16 v[166:169], v[194:197], v[186:189], v[166:169]
	v_mfma_f32_16x16x32_bf16 v[162:165], v[194:197], v[190:193], v[162:165]
	ds_read_b128 v[194:197], v218 offset:4096
	ds_read_b128 v[238:241], v236 offset:16384
	v_mfma_f32_16x16x32_bf16 v[158:161], v[198:201], v[178:181], v[158:161]
	v_mfma_f32_16x16x32_bf16 v[154:157], v[198:201], v[182:185], v[154:157]
	v_mfma_f32_16x16x32_bf16 v[150:153], v[198:201], v[186:189], v[150:153]
	v_mfma_f32_16x16x32_bf16 v[146:149], v[198:201], v[190:193], v[146:149]
	ds_read_b128 v[198:201], v218 offset:5120
	ds_read_b128 v[242:245], v236 offset:17408
	v_mfma_f32_16x16x32_bf16 v[142:145], v[202:205], v[178:181], v[142:145]
	v_mfma_f32_16x16x32_bf16 v[138:141], v[202:205], v[182:185], v[138:141]
	v_mfma_f32_16x16x32_bf16 v[134:137], v[202:205], v[186:189], v[134:137]
	v_mfma_f32_16x16x32_bf16 v[130:133], v[202:205], v[190:193], v[130:133]
	ds_read_b128 v[202:205], v218 offset:6144
	ds_read_b128 v[246:249], v236 offset:18432
	s_waitcnt lgkmcnt(6)
	v_mfma_f32_16x16x32_bf16 v[126:129], v[206:209], v[178:181], v[126:129]
	v_mfma_f32_16x16x32_bf16 v[122:125], v[206:209], v[182:185], v[122:125]
	v_mfma_f32_16x16x32_bf16 v[118:121], v[206:209], v[186:189], v[118:121]
	v_mfma_f32_16x16x32_bf16 v[114:117], v[206:209], v[190:193], v[114:117]
	ds_read_b128 v[206:209], v218 offset:7168
	ds_read_b128 v[222:225], v236 offset:19456
	s_add_i32 s35, s1, s6
	v_add_u32_e32 v218, s35, v218
	s_waitcnt lgkmcnt(7)
	v_mfma_f32_16x16x32_bf16 v[110:113], v[194:197], v[178:181], v[110:113]
	v_mfma_f32_16x16x32_bf16 v[106:109], v[194:197], v[182:185], v[106:109]
	v_mfma_f32_16x16x32_bf16 v[102:105], v[194:197], v[186:189], v[102:105]
	v_mfma_f32_16x16x32_bf16 v[98:101], v[194:197], v[190:193], v[98:101]
	ds_read_b128 v[194:197], v219
	s_waitcnt lgkmcnt(6)
	v_mfma_f32_16x16x32_bf16 v[94:97], v[198:201], v[178:181], v[94:97]
	v_mfma_f32_16x16x32_bf16 v[90:93], v[198:201], v[182:185], v[90:93]
	v_mfma_f32_16x16x32_bf16 v[86:89], v[198:201], v[186:189], v[86:89]
	v_mfma_f32_16x16x32_bf16 v[82:85], v[198:201], v[190:193], v[82:85]
	ds_read_b128 v[198:201], v219 offset:1024
	s_waitcnt lgkmcnt(5)
	v_mfma_f32_16x16x32_bf16 v[78:81], v[202:205], v[178:181], v[78:81]
	v_mfma_f32_16x16x32_bf16 v[74:77], v[202:205], v[182:185], v[74:77]
	v_mfma_f32_16x16x32_bf16 v[70:73], v[202:205], v[186:189], v[70:73]
	v_mfma_f32_16x16x32_bf16 v[66:69], v[202:205], v[190:193], v[66:69]
	ds_read_b128 v[202:205], v219 offset:2048
	s_waitcnt lgkmcnt(4)
	v_mfma_f32_16x16x32_bf16 v[62:65], v[206:209], v[178:181], v[62:65]
	v_mfma_f32_16x16x32_bf16 v[58:61], v[206:209], v[182:185], v[58:61]
	v_mfma_f32_16x16x32_bf16 v[54:57], v[206:209], v[186:189], v[54:57]
	v_mfma_f32_16x16x32_bf16 v[50:53], v[206:209], v[190:193], v[50:53]
	ds_read_b128 v[206:209], v219 offset:3072
	v_add_u32_e32 v236, s6, v236
	s_waitcnt lgkmcnt(1)
	s_barrier
	s_mov_b32 s35, s1
	s_mov_b32 s1, s6
	s_mov_b32 s6, s7
	s_mov_b32 s7, s35
	v_mfma_f32_16x16x32_bf16 v[174:177], v[194:197], v[238:241], v[174:177]
	v_mfma_f32_16x16x32_bf16 v[170:173], v[194:197], v[242:245], v[170:173]
	v_mfma_f32_16x16x32_bf16 v[166:169], v[194:197], v[246:249], v[166:169]
	v_mfma_f32_16x16x32_bf16 v[162:165], v[194:197], v[222:225], v[162:165]
	ds_read_b128 v[194:197], v219 offset:4096
	v_mfma_f32_16x16x32_bf16 v[158:161], v[198:201], v[238:241], v[158:161]
	v_mfma_f32_16x16x32_bf16 v[154:157], v[198:201], v[242:245], v[154:157]
	v_mfma_f32_16x16x32_bf16 v[150:153], v[198:201], v[246:249], v[150:153]
	v_mfma_f32_16x16x32_bf16 v[146:149], v[198:201], v[222:225], v[146:149]
	ds_read_b128 v[198:201], v219 offset:5120
	v_mfma_f32_16x16x32_bf16 v[142:145], v[202:205], v[238:241], v[142:145]
	v_mfma_f32_16x16x32_bf16 v[138:141], v[202:205], v[242:245], v[138:141]
	v_mfma_f32_16x16x32_bf16 v[134:137], v[202:205], v[246:249], v[134:137]
	v_mfma_f32_16x16x32_bf16 v[130:133], v[202:205], v[222:225], v[130:133]
	ds_read_b128 v[202:205], v219 offset:6144
	s_waitcnt lgkmcnt(3)
	v_mfma_f32_16x16x32_bf16 v[126:129], v[206:209], v[238:241], v[126:129]
	v_mfma_f32_16x16x32_bf16 v[122:125], v[206:209], v[242:245], v[122:125]
	v_mfma_f32_16x16x32_bf16 v[118:121], v[206:209], v[246:249], v[118:121]
	v_mfma_f32_16x16x32_bf16 v[114:117], v[206:209], v[222:225], v[114:117]
	ds_read_b128 v[206:209], v219 offset:7168
	s_add_i32 s35, s1, s6
	v_add_u32_e32 v219, s35, v219
	s_waitcnt lgkmcnt(3)
	v_mfma_f32_16x16x32_bf16 v[110:113], v[194:197], v[238:241], v[110:113]
	v_mfma_f32_16x16x32_bf16 v[106:109], v[194:197], v[242:245], v[106:109]
	v_mfma_f32_16x16x32_bf16 v[102:105], v[194:197], v[246:249], v[102:105]
	v_mfma_f32_16x16x32_bf16 v[98:101], v[194:197], v[222:225], v[98:101]
	s_waitcnt lgkmcnt(2)
	v_mfma_f32_16x16x32_bf16 v[94:97], v[198:201], v[238:241], v[94:97]
	v_mfma_f32_16x16x32_bf16 v[90:93], v[198:201], v[242:245], v[90:93]
	v_mfma_f32_16x16x32_bf16 v[86:89], v[198:201], v[246:249], v[86:89]
	v_mfma_f32_16x16x32_bf16 v[82:85], v[198:201], v[222:225], v[82:85]
	s_waitcnt lgkmcnt(1)
	v_mfma_f32_16x16x32_bf16 v[78:81], v[202:205], v[238:241], v[78:81]
	v_mfma_f32_16x16x32_bf16 v[74:77], v[202:205], v[242:245], v[74:77]
	v_mfma_f32_16x16x32_bf16 v[70:73], v[202:205], v[246:249], v[70:73]
	v_mfma_f32_16x16x32_bf16 v[66:69], v[202:205], v[222:225], v[66:69]
	s_waitcnt lgkmcnt(0)
	v_mfma_f32_16x16x32_bf16 v[62:65], v[206:209], v[238:241], v[62:65]
	v_mfma_f32_16x16x32_bf16 v[58:61], v[206:209], v[242:245], v[58:61]
	v_mfma_f32_16x16x32_bf16 v[54:57], v[206:209], v[246:249], v[54:57]
	v_mfma_f32_16x16x32_bf16 v[50:53], v[206:209], v[222:225], v[50:53]
	v_add_u32_e32 v236, s6, v236
	s_barrier
	s_mov_b32 s35, s1
	s_mov_b32 s1, s6
	s_mov_b32 s6, s7
	s_mov_b32 s7, s35
	s_nop 7
	s_branch .LBB0_285

; __device__ __forceinline__ int otid() { int t = threadIdx.x; asm volatile("" : "+v"(t)); return t; }
; template <int MODE>
; __device__ void gemm_tile2(const u16* __restrict__ X, int lda, const u16* __restrict__ W, int ldb, int K,
;                            int m0, int n0, u16* __restrict__ outb, int vbase,
;                            const float* resid, float* outf, unsigned char* smem) {
;     ...
;   const int tid = otid(), lane = tid & 63, l15 = lane & 15, quad = lane >> 4;
;   const int wave = tid >> 6;
;   const int wx = wave >> 1, ww = wave & 1;
;   f32x4 acc[8][4];
; #pragma unroll
;   for (int i = 0; i < 8; ++i)
; #pragma unroll
;     for (int j = 0; j < 4; ++j) acc[i][j] = f32x4{0.f, 0.f, 0.f, 0.f};
;   u32x4 rx[2][4], rw[2][2];
;   const int lrow = tid >> 2, lkc = (tid & 3) * 8;
;   const int lsw = ((tid & 3) ^ ((0 - (lrow >> 2)) & 3)) * 8;
;   const int fsw = (quad ^ ((0 - (l15 >> 2)) & 3)) * 8;
;   const auto rsX = __builtin_amdgcn_make_buffer_rsrc((void*)(X + (size_t)m0 * lda), (short)0, 0x7fffffff, 0x00020000);
;   const auto rsW = __builtin_amdgcn_make_buffer_rsrc((void*)(W + (size_t)n0 * ldb), (short)0, 0x7fffffff, 0x00020000);
;   const int vox = (lrow * lda + lkc) * 2, vow = (lrow * ldb + lkc) * 2;
;   const int nk = K / 32;
;     ...
;   G2_GLOAD(0, 0);
;   G2_GLOAD(1, 1);
;   __syncthreads();
;   G2_LSTORE(0, 0);
;   G2_GLOAD(0, 2);
;   __syncthreads();
; __device__ void phase_outproj(const Params& p, int layer, unsigned char* smem) {
;     ...
;   const int xcd = blockIdx.x & 7, loc = blockIdx.x >> 3, nloc = gridDim.x >> 3;
;   for (int idx = loc; idx < 8 * 8; idx += nloc) {
;     int nt = idx >> 3, mt = xcd * 8 + (idx & 7);
;     gemm_tile2<2>(P_XN, DM, W, DM, DM, mt * 256, nt * 128, nullptr, 0, resid, p.out, smem);
.LBB0_337:
	s_and_b32 s6, s18, 7
	v_readlane_b32 s7, v254, 16
	s_or_b32 s29, s6, s7
	s_lshl_b32 s6, s18, 4
	s_and_b32 s19, s6, 0x380
	s_lshl_b32 s7, s29, 19
	s_add_u32 s24, s36, s7
	v_mov_b32_e32 v230, v210
	s_addc_u32 s7, s37, 0
	s_and_b32 s25, s7, 0xffff
	s_lshl_b32 s7, s19, 11
	s_add_u32 s40, s8, s7
	s_addc_u32 s7, s9, 0
	s_and_b32 s41, s7, 0xffff
	s_mov_b32 s42, s26
	s_mov_b32 s43, s27
	v_lshrrev_b32_e32 v0, 4, v230
	v_and_b32_e32 v231, 15, v230
	v_bfe_u32 v233, v230, 6, 1
	v_lshrrev_b32_e32 v2, 2, v230
	v_lshrrev_b32_e32 v3, 4, v230
	v_sub_u32_e32 v4, 0, v3
	v_xor_b32_e32 v4, v230, v4
	v_lshlrev_b32_e32 v4, 4, v4
	v_and_b32_e32 v4, 48, v4
	v_lshl_or_b32 v234, v2, 6, v4
	v_lshlrev_b32_e32 v4, 4, v230
	v_and_b32_e32 v4, 48, v4
	v_lshl_or_b32 v232, v2, 11, v4
	v_sub_u32_e32 v4, 0, v2
	v_xor_b32_e32 v4, v3, v4
	v_lshlrev_b32_e32 v4, 4, v4
	v_and_b32_e32 v4, 48, v4
	v_lshlrev_b32_e32 v5, 6, v230
	v_and_b32_e32 v6, 0x3c0, v5
	v_bfe_u32 v7, v230, 6, 1
	v_lshl_or_b32 v7, v7, 12, v4
	v_add_u32_e32 v235, v7, v6
	v_and_b32_e32 v5, 0xffffe3c0, v5
	v_add_u32_e32 v218, v4, v5
	v_add_u32_e32 v219, 0x6000, v218
	buffer_load_dwordx4 v[130:133], v232, s[24:27], 0 offen
	buffer_load_dwordx4 v[134:137], v232, s[24:27], s27 offen
	buffer_load_dwordx4 v[138:141], v232, s[24:27], s77 offen
	buffer_load_dwordx4 v[142:145], v232, s[24:27], s78 offen
	buffer_load_dwordx4 v[146:149], v232, s[40:43], 0 offen
	buffer_load_dwordx4 v[150:153], v232, s[40:43], s27 offen
	v_add_u32_e32 v232, 64, v232
	buffer_load_dwordx4 v[154:157], v232, s[24:27], 0 offen
	buffer_load_dwordx4 v[158:161], v232, s[24:27], s27 offen
	buffer_load_dwordx4 v[162:165], v232, s[24:27], s77 offen
	buffer_load_dwordx4 v[166:169], v232, s[24:27], s78 offen
	buffer_load_dwordx4 v[170:173], v232, s[40:43], 0 offen
	buffer_load_dwordx4 v[174:177], v232, s[40:43], s27 offen
	v_add_u32_e32 v232, 64, v232
	v_mov_b32_e32 v2, 0
	v_mov_b32_e32 v3, 0
	v_mov_b32_e32 v4, 0
	v_mov_b32_e32 v5, 0
	v_mov_b32_e32 v6, 0
	v_mov_b32_e32 v7, 0
	v_mov_b32_e32 v8, 0
	v_mov_b32_e32 v9, 0
	v_mov_b32_e32 v10, 0
	v_mov_b32_e32 v11, 0
	v_mov_b32_e32 v12, 0
	v_mov_b32_e32 v13, 0
	v_mov_b32_e32 v14, 0
	v_mov_b32_e32 v15, 0
	v_mov_b32_e32 v16, 0
	v_mov_b32_e32 v17, 0
	v_mov_b32_e32 v18, 0
	v_mov_b32_e32 v19, 0
	v_mov_b32_e32 v20, 0
	v_mov_b32_e32 v21, 0
	v_mov_b32_e32 v22, 0
	v_mov_b32_e32 v23, 0
	v_mov_b32_e32 v24, 0
	v_mov_b32_e32 v25, 0
	v_mov_b32_e32 v26, 0
	v_mov_b32_e32 v27, 0
	v_mov_b32_e32 v28, 0
	v_mov_b32_e32 v29, 0
	v_mov_b32_e32 v30, 0
	v_mov_b32_e32 v31, 0
	v_mov_b32_e32 v32, 0
	v_mov_b32_e32 v33, 0
	v_mov_b32_e32 v34, 0
	v_mov_b32_e32 v35, 0
	v_mov_b32_e32 v36, 0
	v_mov_b32_e32 v37, 0
	v_mov_b32_e32 v38, 0
	v_mov_b32_e32 v39, 0
	v_mov_b32_e32 v40, 0
	v_mov_b32_e32 v41, 0
	v_mov_b32_e32 v42, 0
	v_mov_b32_e32 v43, 0
	v_mov_b32_e32 v44, 0
	v_mov_b32_e32 v45, 0
	v_mov_b32_e32 v46, 0
	v_mov_b32_e32 v47, 0
	v_mov_b32_e32 v48, 0
	v_mov_b32_e32 v49, 0
	v_mov_b32_e32 v50, 0
	v_mov_b32_e32 v51, 0
	v_mov_b32_e32 v52, 0
	v_mov_b32_e32 v53, 0
	v_mov_b32_e32 v54, 0
	v_mov_b32_e32 v55, 0
	v_mov_b32_e32 v56, 0
	v_mov_b32_e32 v57, 0
	v_mov_b32_e32 v58, 0
	v_mov_b32_e32 v59, 0
	v_mov_b32_e32 v60, 0
	v_mov_b32_e32 v61, 0
	v_mov_b32_e32 v62, 0
	v_mov_b32_e32 v63, 0
	v_mov_b32_e32 v64, 0
	v_mov_b32_e32 v65, 0
	v_mov_b32_e32 v66, 0
	v_mov_b32_e32 v67, 0
	v_mov_b32_e32 v68, 0
	v_mov_b32_e32 v69, 0
	v_mov_b32_e32 v70, 0
	v_mov_b32_e32 v71, 0
	v_mov_b32_e32 v72, 0
	v_mov_b32_e32 v73, 0
	v_mov_b32_e32 v74, 0
	v_mov_b32_e32 v75, 0
	v_mov_b32_e32 v76, 0
	v_mov_b32_e32 v77, 0
	v_mov_b32_e32 v78, 0
	v_mov_b32_e32 v79, 0
	v_mov_b32_e32 v80, 0
	v_mov_b32_e32 v81, 0
	v_mov_b32_e32 v82, 0
	v_mov_b32_e32 v83, 0
	v_mov_b32_e32 v84, 0
	v_mov_b32_e32 v85, 0
	v_mov_b32_e32 v86, 0
	v_mov_b32_e32 v87, 0
	v_mov_b32_e32 v88, 0
	v_mov_b32_e32 v89, 0
	v_mov_b32_e32 v90, 0
	v_mov_b32_e32 v91, 0
	v_mov_b32_e32 v92, 0
	v_mov_b32_e32 v93, 0
	v_mov_b32_e32 v94, 0
	v_mov_b32_e32 v95, 0
	v_mov_b32_e32 v96, 0
	v_mov_b32_e32 v97, 0
	v_mov_b32_e32 v98, 0
	v_mov_b32_e32 v99, 0
	v_mov_b32_e32 v100, 0
	v_mov_b32_e32 v101, 0
	v_mov_b32_e32 v102, 0
	v_mov_b32_e32 v103, 0
	v_mov_b32_e32 v104, 0
	v_mov_b32_e32 v105, 0
	v_mov_b32_e32 v106, 0
	v_mov_b32_e32 v107, 0
	v_mov_b32_e32 v108, 0
	v_mov_b32_e32 v109, 0
	v_mov_b32_e32 v110, 0
	v_mov_b32_e32 v111, 0
	v_mov_b32_e32 v112, 0
	v_mov_b32_e32 v113, 0
	v_mov_b32_e32 v114, 0
	v_mov_b32_e32 v115, 0
	v_mov_b32_e32 v116, 0
	v_mov_b32_e32 v117, 0
	v_mov_b32_e32 v118, 0
	v_mov_b32_e32 v119, 0
	v_mov_b32_e32 v120, 0
	v_mov_b32_e32 v121, 0
	v_mov_b32_e32 v122, 0
	v_mov_b32_e32 v123, 0
	v_mov_b32_e32 v124, 0
	v_mov_b32_e32 v125, 0
	v_mov_b32_e32 v126, 0
	v_mov_b32_e32 v127, 0
	v_mov_b32_e32 v128, 0
	v_mov_b32_e32 v129, 0
	s_mov_b32 s7, 0x6000
	s_mov_b32 s30, 0x6000
	s_mov_b32 s31, 0xffff4000
	s_mov_b32 s6, 0
	s_barrier
	s_waitcnt vmcnt(6)
	ds_write_b128 v234, v[130:133]
	ds_write_b128 v234, v[134:137] offset:4096
	ds_write_b128 v234, v[138:141] offset:8192
	ds_write_b128 v234, v[142:145] offset:12288
	ds_write_b128 v234, v[146:149] offset:16384
	ds_write_b128 v234, v[150:153] offset:20480
	buffer_load_dwordx4 v[130:133], v232, s[24:27], 0 offen
	buffer_load_dwordx4 v[134:137], v232, s[24:27], s27 offen
	buffer_load_dwordx4 v[138:141], v232, s[24:27], s77 offen
	buffer_load_dwordx4 v[142:145], v232, s[24:27], s78 offen
	buffer_load_dwordx4 v[146:149], v232, s[40:43], 0 offen
	buffer_load_dwordx4 v[150:153], v232, s[40:43], s27 offen
	v_add_u32_e32 v232, 64, v232
	v_add_u32_e32 v234, 0x6000, v234
	s_waitcnt vmcnt(6)
	ds_write_b128 v234, v[154:157]
	ds_write_b128 v234, v[158:161] offset:4096
	ds_write_b128 v234, v[162:165] offset:8192
	ds_write_b128 v234, v[166:169] offset:12288
	ds_write_b128 v234, v[170:173] offset:16384
	ds_write_b128 v234, v[174:177] offset:20480
	buffer_load_dwordx4 v[154:157], v232, s[24:27], 0 offen
	buffer_load_dwordx4 v[158:161], v232, s[24:27], s27 offen
	buffer_load_dwordx4 v[162:165], v232, s[24:27], s77 offen
	buffer_load_dwordx4 v[166:169], v232, s[24:27], s78 offen
	buffer_load_dwordx4 v[170:173], v232, s[40:43], 0 offen
	buffer_load_dwordx4 v[174:177], v232, s[40:43], s27 offen
	v_add_u32_e32 v232, 64, v232
	v_add_u32_e32 v234, 0x6000, v234
	s_waitcnt lgkmcnt(0)
	s_barrier
	ds_read_b128 v[178:181], v235 offset:16384
	ds_read_b128 v[182:185], v235 offset:17408
	ds_read_b128 v[186:189], v235 offset:18432
	ds_read_b128 v[190:193], v235 offset:19456
	v_add_u32_e32 v235, 0x6000, v235
	ds_read_b128 v[194:197], v218
	ds_read_b128 v[198:201], v218 offset:1024
	ds_read_b128 v[202:205], v218 offset:2048
	ds_read_b128 v[206:209], v218 offset:3072
	s_waitcnt lgkmcnt(0)
; template <int MODE>
; __device__ void gemm_tile2(const u16* __restrict__ X, int lda, const u16* __restrict__ W, int ldb, int K,
;                            int m0, int n0, u16* __restrict__ outb, int vbase,
;                            const float* resid, float* outf, unsigned char* smem) {
;     ...
;   for (int kt2 = 0; kt2 < nk; kt2 += 2) {
; #pragma unroll
;     for (int h = 0; h < 2; ++h) {
;       const int kt = kt2 + h;
;       const u16* st = sbase + h * G2STAGE;
;       bf16x8 fw[4], fx[4];
; #pragma unroll
;       for (int j = 0; j < 4; ++j) fw[j] = *(const bf16x8*)(st + 256 * G2S + (ww * 64 + j * 16 + l15) * G2S + fsw);
; #pragma unroll
;       for (int i = 0; i < 4; ++i) fx[i] = *(const bf16x8*)(st + (wx * 128 + i * 16 + l15) * G2S + fsw);
;       __builtin_amdgcn_sched_barrier(0);
;       __builtin_amdgcn_s_setprio(1);
; #pragma unroll
;       for (int i = 0; i < 4; ++i) {
; #pragma unroll
;         for (int j = 0; j < 4; ++j) {
;           if (MODE == 1) acc[i][j] = mfma16(fx[i], fw[j], acc[i][j]);
;           else acc[i][j] = mfma16(fw[j], fx[i], acc[i][j]);
;         }
;       }
;       __builtin_amdgcn_s_setprio(0);
;       __builtin_amdgcn_sched_barrier(0);
; #pragma unroll
;       for (int i = 0; i < 4; ++i) fx[i] = *(const bf16x8*)(st + (wx * 128 + (i + 4) * 16 + l15) * G2S + fsw);
;       __builtin_amdgcn_sched_barrier(0);
;       if (kt + 1 < nk) G2_LSTORE(1 - h, 1 - h);
;       if (kt + 3 < nk) G2_GLOAD(1 - h, kt + 3);
;       __builtin_amdgcn_sched_barrier(0);
;       __builtin_amdgcn_s_setprio(1);
; #pragma unroll
;       for (int i = 0; i < 4; ++i) {
; #pragma unroll
;         for (int j = 0; j < 4; ++j) {
;           if (MODE == 1) acc[i + 4][j] = mfma16(fx[i], fw[j], acc[i + 4][j]);
;           else acc[i + 4][j] = mfma16(fw[j], fx[i], acc[i + 4][j]);
;         }
;       }
;       __builtin_amdgcn_s_setprio(0);
;       __syncthreads();
;     }
;   }
.Lh2_loop:
	v_mfma_f32_16x16x32_bf16 v[126:129], v[178:181], v[194:197], v[126:129]
	v_mfma_f32_16x16x32_bf16 v[122:125], v[182:185], v[194:197], v[122:125]
	v_mfma_f32_16x16x32_bf16 v[118:121], v[186:189], v[194:197], v[118:121]
	v_mfma_f32_16x16x32_bf16 v[114:117], v[190:193], v[194:197], v[114:117]
	ds_read_b128 v[194:197], v218 offset:4096
	ds_read_b128 v[238:241], v235 offset:16384
	v_mfma_f32_16x16x32_bf16 v[110:113], v[178:181], v[198:201], v[110:113]
	v_mfma_f32_16x16x32_bf16 v[106:109], v[182:185], v[198:201], v[106:109]
	v_mfma_f32_16x16x32_bf16 v[102:105], v[186:189], v[198:201], v[102:105]
	v_mfma_f32_16x16x32_bf16 v[98:101], v[190:193], v[198:201], v[98:101]
	ds_read_b128 v[198:201], v218 offset:5120
	ds_read_b128 v[242:245], v235 offset:17408
	v_mfma_f32_16x16x32_bf16 v[94:97], v[178:181], v[202:205], v[94:97]
	v_mfma_f32_16x16x32_bf16 v[90:93], v[182:185], v[202:205], v[90:93]
	v_mfma_f32_16x16x32_bf16 v[86:89], v[186:189], v[202:205], v[86:89]
	v_mfma_f32_16x16x32_bf16 v[82:85], v[190:193], v[202:205], v[82:85]
	ds_read_b128 v[202:205], v218 offset:6144
	ds_read_b128 v[246:249], v235 offset:18432
	s_waitcnt lgkmcnt(6)
	v_mfma_f32_16x16x32_bf16 v[78:81], v[178:181], v[206:209], v[78:81]
	v_mfma_f32_16x16x32_bf16 v[74:77], v[182:185], v[206:209], v[74:77]
	v_mfma_f32_16x16x32_bf16 v[70:73], v[186:189], v[206:209], v[70:73]
	v_mfma_f32_16x16x32_bf16 v[66:69], v[190:193], v[206:209], v[66:69]
	ds_read_b128 v[206:209], v218 offset:7168
	ds_read_b128 v[222:225], v235 offset:19456
	s_add_i32 s35, s7, s30
	v_add_u32_e32 v218, s35, v218
	s_waitcnt lgkmcnt(7)
	v_mfma_f32_16x16x32_bf16 v[62:65], v[178:181], v[194:197], v[62:65]
	v_mfma_f32_16x16x32_bf16 v[58:61], v[182:185], v[194:197], v[58:61]
	v_mfma_f32_16x16x32_bf16 v[54:57], v[186:189], v[194:197], v[54:57]
	v_mfma_f32_16x16x32_bf16 v[50:53], v[190:193], v[194:197], v[50:53]
	ds_read_b128 v[194:197], v219
	s_waitcnt vmcnt(6)
	ds_write_b128 v234, v[130:133]
	ds_write_b128 v234, v[134:137] offset:4096
	s_waitcnt lgkmcnt(8)
	v_mfma_f32_16x16x32_bf16 v[46:49], v[178:181], v[198:201], v[46:49]
	v_mfma_f32_16x16x32_bf16 v[42:45], v[182:185], v[198:201], v[42:45]
	v_mfma_f32_16x16x32_bf16 v[38:41], v[186:189], v[198:201], v[38:41]
	v_mfma_f32_16x16x32_bf16 v[34:37], v[190:193], v[198:201], v[34:37]
	ds_read_b128 v[198:201], v219 offset:1024
	ds_write_b128 v234, v[138:141] offset:8192
	ds_write_b128 v234, v[142:145] offset:12288
	s_waitcnt lgkmcnt(9)
	v_mfma_f32_16x16x32_bf16 v[30:33], v[178:181], v[202:205], v[30:33]
	v_mfma_f32_16x16x32_bf16 v[26:29], v[182:185], v[202:205], v[26:29]
	v_mfma_f32_16x16x32_bf16 v[22:25], v[186:189], v[202:205], v[22:25]
	v_mfma_f32_16x16x32_bf16 v[18:21], v[190:193], v[202:205], v[18:21]
	ds_read_b128 v[202:205], v219 offset:2048
	ds_write_b128 v234, v[146:149] offset:16384
	ds_write_b128 v234, v[150:153] offset:20480
	v_add_u32_e32 v234, s31, v234
	s_waitcnt lgkmcnt(10)
	v_mfma_f32_16x16x32_bf16 v[14:17], v[178:181], v[206:209], v[14:17]
	v_mfma_f32_16x16x32_bf16 v[10:13], v[182:185], v[206:209], v[10:13]
	v_mfma_f32_16x16x32_bf16 v[6:9], v[186:189], v[206:209], v[6:9]
	v_mfma_f32_16x16x32_bf16 v[2:5], v[190:193], v[206:209], v[2:5]
	ds_read_b128 v[206:209], v219 offset:3072
	v_add_u32_e32 v235, s30, v235
	buffer_load_dwordx4 v[130:133], v232, s[24:27], 0 offen
	buffer_load_dwordx4 v[134:137], v232, s[24:27], s27 offen
	buffer_load_dwordx4 v[138:141], v232, s[24:27], s77 offen
	buffer_load_dwordx4 v[142:145], v232, s[24:27], s78 offen
	buffer_load_dwordx4 v[146:149], v232, s[40:43], 0 offen
	buffer_load_dwordx4 v[150:153], v232, s[40:43], s27 offen
	v_add_u32_e32 v232, 64, v232
	s_waitcnt lgkmcnt(1)
	s_barrier
	s_mov_b32 s35, s7
	s_mov_b32 s7, s30
	s_mov_b32 s30, s31
	s_mov_b32 s31, s35
	v_mfma_f32_16x16x32_bf16 v[126:129], v[238:241], v[194:197], v[126:129]
	v_mfma_f32_16x16x32_bf16 v[122:125], v[242:245], v[194:197], v[122:125]
	v_mfma_f32_16x16x32_bf16 v[118:121], v[246:249], v[194:197], v[118:121]
	v_mfma_f32_16x16x32_bf16 v[114:117], v[222:225], v[194:197], v[114:117]
	ds_read_b128 v[194:197], v219 offset:4096
	ds_read_b128 v[178:181], v235 offset:16384
	v_mfma_f32_16x16x32_bf16 v[110:113], v[238:241], v[198:201], v[110:113]
	v_mfma_f32_16x16x32_bf16 v[106:109], v[242:245], v[198:201], v[106:109]
	v_mfma_f32_16x16x32_bf16 v[102:105], v[246:249], v[198:201], v[102:105]
	v_mfma_f32_16x16x32_bf16 v[98:101], v[222:225], v[198:201], v[98:101]
	ds_read_b128 v[198:201], v219 offset:5120
	ds_read_b128 v[182:185], v235 offset:17408
	v_mfma_f32_16x16x32_bf16 v[94:97], v[238:241], v[202:205], v[94:97]
	v_mfma_f32_16x16x32_bf16 v[90:93], v[242:245], v[202:205], v[90:93]
	v_mfma_f32_16x16x32_bf16 v[86:89], v[246:249], v[202:205], v[86:89]
	v_mfma_f32_16x16x32_bf16 v[82:85], v[222:225], v[202:205], v[82:85]
	ds_read_b128 v[202:205], v219 offset:6144
	ds_read_b128 v[186:189], v235 offset:18432
	s_waitcnt lgkmcnt(6)
	v_mfma_f32_16x16x32_bf16 v[78:81], v[238:241], v[206:209], v[78:81]
	v_mfma_f32_16x16x32_bf16 v[74:77], v[242:245], v[206:209], v[74:77]
	v_mfma_f32_16x16x32_bf16 v[70:73], v[246:249], v[206:209], v[70:73]
	v_mfma_f32_16x16x32_bf16 v[66:69], v[222:225], v[206:209], v[66:69]
	ds_read_b128 v[206:209], v219 offset:7168
	ds_read_b128 v[190:193], v235 offset:19456
	s_add_i32 s35, s7, s30
	v_add_u32_e32 v219, s35, v219
	s_waitcnt lgkmcnt(7)
	v_mfma_f32_16x16x32_bf16 v[62:65], v[238:241], v[194:197], v[62:65]
	v_mfma_f32_16x16x32_bf16 v[58:61], v[242:245], v[194:197], v[58:61]
	v_mfma_f32_16x16x32_bf16 v[54:57], v[246:249], v[194:197], v[54:57]
	v_mfma_f32_16x16x32_bf16 v[50:53], v[222:225], v[194:197], v[50:53]
	ds_read_b128 v[194:197], v218
	s_waitcnt vmcnt(6)
; template <int MODE>
; __device__ void gemm_tile2(const u16* __restrict__ X, int lda, const u16* __restrict__ W, int ldb, int K,
;                            int m0, int n0, u16* __restrict__ outb, int vbase,
;                            const float* resid, float* outf, unsigned char* smem) {
;     ...
;   for (int kt2 = 0; kt2 < nk; kt2 += 2) {
; #pragma unroll
;     for (int h = 0; h < 2; ++h) {
;       const int kt = kt2 + h;
;       const u16* st = sbase + h * G2STAGE;
;       bf16x8 fw[4], fx[4];
; #pragma unroll
;       for (int j = 0; j < 4; ++j) fw[j] = *(const bf16x8*)(st + 256 * G2S + (ww * 64 + j * 16 + l15) * G2S + fsw);
; #pragma unroll
;       for (int i = 0; i < 4; ++i) fx[i] = *(const bf16x8*)(st + (wx * 128 + i * 16 + l15) * G2S + fsw);
;       __builtin_amdgcn_sched_barrier(0);
;       __builtin_amdgcn_s_setprio(1);
; #pragma unroll
;       for (int i = 0; i < 4; ++i) {
; #pragma unroll
;         for (int j = 0; j < 4; ++j) {
;           if (MODE == 1) acc[i][j] = mfma16(fx[i], fw[j], acc[i][j]);
;           else acc[i][j] = mfma16(fw[j], fx[i], acc[i][j]);
;         }
;       }
;       __builtin_amdgcn_s_setprio(0);
;       __builtin_amdgcn_sched_barrier(0);
; #pragma unroll
;       for (int i = 0; i < 4; ++i) fx[i] = *(const bf16x8*)(st + (wx * 128 + (i + 4) * 16 + l15) * G2S + fsw);
;       __builtin_amdgcn_sched_barrier(0);
;       if (kt + 1 < nk) G2_LSTORE(1 - h, 1 - h);
;       if (kt + 3 < nk) G2_GLOAD(1 - h, kt + 3);
;       __builtin_amdgcn_sched_barrier(0);
;       __builtin_amdgcn_s_setprio(1);
; #pragma unroll
;       for (int i = 0; i < 4; ++i) {
; #pragma unroll
;         for (int j = 0; j < 4; ++j) {
;           if (MODE == 1) acc[i + 4][j] = mfma16(fx[i], fw[j], acc[i + 4][j]);
;           else acc[i + 4][j] = mfma16(fw[j], fx[i], acc[i + 4][j]);
;         }
;       }
;       __builtin_amdgcn_s_setprio(0);
;       __syncthreads();
;     }
;   }
	ds_write_b128 v234, v[154:157]
	ds_write_b128 v234, v[158:161] offset:4096
	s_waitcnt lgkmcnt(8)
	v_mfma_f32_16x16x32_bf16 v[46:49], v[238:241], v[198:201], v[46:49]
	v_mfma_f32_16x16x32_bf16 v[42:45], v[242:245], v[198:201], v[42:45]
	v_mfma_f32_16x16x32_bf16 v[38:41], v[246:249], v[198:201], v[38:41]
	v_mfma_f32_16x16x32_bf16 v[34:37], v[222:225], v[198:201], v[34:37]
	ds_read_b128 v[198:201], v218 offset:1024
	ds_write_b128 v234, v[162:165] offset:8192
	ds_write_b128 v234, v[166:169] offset:12288
	s_waitcnt lgkmcnt(9)
	v_mfma_f32_16x16x32_bf16 v[30:33], v[238:241], v[202:205], v[30:33]
	v_mfma_f32_16x16x32_bf16 v[26:29], v[242:245], v[202:205], v[26:29]
	v_mfma_f32_16x16x32_bf16 v[22:25], v[246:249], v[202:205], v[22:25]
	v_mfma_f32_16x16x32_bf16 v[18:21], v[222:225], v[202:205], v[18:21]
	ds_read_b128 v[202:205], v218 offset:2048
	ds_write_b128 v234, v[170:173] offset:16384
	ds_write_b128 v234, v[174:177] offset:20480
	v_add_u32_e32 v234, s31, v234
	s_waitcnt lgkmcnt(10)
	v_mfma_f32_16x16x32_bf16 v[14:17], v[238:241], v[206:209], v[14:17]
	v_mfma_f32_16x16x32_bf16 v[10:13], v[242:245], v[206:209], v[10:13]
	v_mfma_f32_16x16x32_bf16 v[6:9], v[246:249], v[206:209], v[6:9]
	v_mfma_f32_16x16x32_bf16 v[2:5], v[222:225], v[206:209], v[2:5]
	ds_read_b128 v[206:209], v218 offset:3072
	v_add_u32_e32 v235, s30, v235
	buffer_load_dwordx4 v[154:157], v232, s[24:27], 0 offen
	buffer_load_dwordx4 v[158:161], v232, s[24:27], s27 offen
	buffer_load_dwordx4 v[162:165], v232, s[24:27], s77 offen
	buffer_load_dwordx4 v[166:169], v232, s[24:27], s78 offen
	buffer_load_dwordx4 v[170:173], v232, s[40:43], 0 offen
	buffer_load_dwordx4 v[174:177], v232, s[40:43], s27 offen
	v_add_u32_e32 v232, 64, v232
	s_waitcnt lgkmcnt(1)
	s_barrier
	s_mov_b32 s35, s7
	s_mov_b32 s7, s30
	s_mov_b32 s30, s31
	s_mov_b32 s31, s35
	s_add_u32 s6, s6, 2
	s_cmp_lt_u32 s6, 28
	s_cbranch_scc1 .Lh2_loop
	v_mfma_f32_16x16x32_bf16 v[126:129], v[178:181], v[194:197], v[126:129]
	v_mfma_f32_16x16x32_bf16 v[122:125], v[182:185], v[194:197], v[122:125]
	v_mfma_f32_16x16x32_bf16 v[118:121], v[186:189], v[194:197], v[118:121]
	v_mfma_f32_16x16x32_bf16 v[114:117], v[190:193], v[194:197], v[114:117]
	ds_read_b128 v[194:197], v218 offset:4096
	ds_read_b128 v[238:241], v235 offset:16384
	v_mfma_f32_16x16x32_bf16 v[110:113], v[178:181], v[198:201], v[110:113]
	v_mfma_f32_16x16x32_bf16 v[106:109], v[182:185], v[198:201], v[106:109]
	v_mfma_f32_16x16x32_bf16 v[102:105], v[186:189], v[198:201], v[102:105]
	v_mfma_f32_16x16x32_bf16 v[98:101], v[190:193], v[198:201], v[98:101]
	ds_read_b128 v[198:201], v218 offset:5120
	ds_read_b128 v[242:245], v235 offset:17408
	v_mfma_f32_16x16x32_bf16 v[94:97], v[178:181], v[202:205], v[94:97]
	v_mfma_f32_16x16x32_bf16 v[90:93], v[182:185], v[202:205], v[90:93]
	v_mfma_f32_16x16x32_bf16 v[86:89], v[186:189], v[202:205], v[86:89]
	v_mfma_f32_16x16x32_bf16 v[82:85], v[190:193], v[202:205], v[82:85]
	ds_read_b128 v[202:205], v218 offset:6144
	ds_read_b128 v[246:249], v235 offset:18432
	s_waitcnt lgkmcnt(6)
	v_mfma_f32_16x16x32_bf16 v[78:81], v[178:181], v[206:209], v[78:81]
	v_mfma_f32_16x16x32_bf16 v[74:77], v[182:185], v[206:209], v[74:77]
	v_mfma_f32_16x16x32_bf16 v[70:73], v[186:189], v[206:209], v[70:73]
	v_mfma_f32_16x16x32_bf16 v[66:69], v[190:193], v[206:209], v[66:69]
	ds_read_b128 v[206:209], v218 offset:7168
	ds_read_b128 v[222:225], v235 offset:19456
	s_add_i32 s35, s7, s30
	v_add_u32_e32 v218, s35, v218
	s_waitcnt lgkmcnt(7)
	v_mfma_f32_16x16x32_bf16 v[62:65], v[178:181], v[194:197], v[62:65]
	v_mfma_f32_16x16x32_bf16 v[58:61], v[182:185], v[194:197], v[58:61]
	v_mfma_f32_16x16x32_bf16 v[54:57], v[186:189], v[194:197], v[54:57]
	v_mfma_f32_16x16x32_bf16 v[50:53], v[190:193], v[194:197], v[50:53]
	ds_read_b128 v[194:197], v219
	s_waitcnt vmcnt(6)
	ds_write_b128 v234, v[130:133]
	ds_write_b128 v234, v[134:137] offset:4096
	s_waitcnt lgkmcnt(8)
	v_mfma_f32_16x16x32_bf16 v[46:49], v[178:181], v[198:201], v[46:49]
	v_mfma_f32_16x16x32_bf16 v[42:45], v[182:185], v[198:201], v[42:45]
	v_mfma_f32_16x16x32_bf16 v[38:41], v[186:189], v[198:201], v[38:41]
	v_mfma_f32_16x16x32_bf16 v[34:37], v[190:193], v[198:201], v[34:37]
	ds_read_b128 v[198:201], v219 offset:1024
	ds_write_b128 v234, v[138:141] offset:8192
	ds_write_b128 v234, v[142:145] offset:12288
	s_waitcnt lgkmcnt(9)
	v_mfma_f32_16x16x32_bf16 v[30:33], v[178:181], v[202:205], v[30:33]
	v_mfma_f32_16x16x32_bf16 v[26:29], v[182:185], v[202:205], v[26:29]
	v_mfma_f32_16x16x32_bf16 v[22:25], v[186:189], v[202:205], v[22:25]
	v_mfma_f32_16x16x32_bf16 v[18:21], v[190:193], v[202:205], v[18:21]
	ds_read_b128 v[202:205], v219 offset:2048
	ds_write_b128 v234, v[146:149] offset:16384
	ds_write_b128 v234, v[150:153] offset:20480
	v_add_u32_e32 v234, s31, v234
	s_waitcnt lgkmcnt(10)
	v_mfma_f32_16x16x32_bf16 v[14:17], v[178:181], v[206:209], v[14:17]
	v_mfma_f32_16x16x32_bf16 v[10:13], v[182:185], v[206:209], v[10:13]
	v_mfma_f32_16x16x32_bf16 v[6:9], v[186:189], v[206:209], v[6:9]
	v_mfma_f32_16x16x32_bf16 v[2:5], v[190:193], v[206:209], v[2:5]
	ds_read_b128 v[206:209], v219 offset:3072
	v_add_u32_e32 v235, s30, v235
	s_waitcnt lgkmcnt(1)
	s_barrier
; template <int MODE>
; __device__ void gemm_tile2(const u16* __restrict__ X, int lda, const u16* __restrict__ W, int ldb, int K,
;                            int m0, int n0, u16* __restrict__ outb, int vbase,
;                            const float* resid, float* outf, unsigned char* smem) {
;     ...
;   for (int kt2 = 0; kt2 < nk; kt2 += 2) {
; #pragma unroll
;     for (int h = 0; h < 2; ++h) {
;       const int kt = kt2 + h;
;       const u16* st = sbase + h * G2STAGE;
;       bf16x8 fw[4], fx[4];
; #pragma unroll
;       for (int j = 0; j < 4; ++j) fw[j] = *(const bf16x8*)(st + 256 * G2S + (ww * 64 + j * 16 + l15) * G2S + fsw);
; #pragma unroll
;       for (int i = 0; i < 4; ++i) fx[i] = *(const bf16x8*)(st + (wx * 128 + i * 16 + l15) * G2S + fsw);
;       __builtin_amdgcn_sched_barrier(0);
;       __builtin_amdgcn_s_setprio(1);
; #pragma unroll
;       for (int i = 0; i < 4; ++i) {
; #pragma unroll
;         for (int j = 0; j < 4; ++j) {
;           if (MODE == 1) acc[i][j] = mfma16(fx[i], fw[j], acc[i][j]);
;           else acc[i][j] = mfma16(fw[j], fx[i], acc[i][j]);
;         }
;       }
;       __builtin_amdgcn_s_setprio(0);
;       __builtin_amdgcn_sched_barrier(0);
; #pragma unroll
;       for (int i = 0; i < 4; ++i) fx[i] = *(const bf16x8*)(st + (wx * 128 + (i + 4) * 16 + l15) * G2S + fsw);
;       __builtin_amdgcn_sched_barrier(0);
;       if (kt + 1 < nk) G2_LSTORE(1 - h, 1 - h);
;       if (kt + 3 < nk) G2_GLOAD(1 - h, kt + 3);
;       __builtin_amdgcn_sched_barrier(0);
;       __builtin_amdgcn_s_setprio(1);
; #pragma unroll
;       for (int i = 0; i < 4; ++i) {
; #pragma unroll
;         for (int j = 0; j < 4; ++j) {
;           if (MODE == 1) acc[i + 4][j] = mfma16(fx[i], fw[j], acc[i + 4][j]);
;           else acc[i + 4][j] = mfma16(fw[j], fx[i], acc[i + 4][j]);
;         }
;       }
;       __builtin_amdgcn_s_setprio(0);
;       __syncthreads();
;     }
;   }
	s_mov_b32 s35, s7
	s_mov_b32 s7, s30
	s_mov_b32 s30, s31
	s_mov_b32 s31, s35
	v_mfma_f32_16x16x32_bf16 v[126:129], v[238:241], v[194:197], v[126:129]
	v_mfma_f32_16x16x32_bf16 v[122:125], v[242:245], v[194:197], v[122:125]
	v_mfma_f32_16x16x32_bf16 v[118:121], v[246:249], v[194:197], v[118:121]
	v_mfma_f32_16x16x32_bf16 v[114:117], v[222:225], v[194:197], v[114:117]
	ds_read_b128 v[194:197], v219 offset:4096
	ds_read_b128 v[178:181], v235 offset:16384
	v_mfma_f32_16x16x32_bf16 v[110:113], v[238:241], v[198:201], v[110:113]
	v_mfma_f32_16x16x32_bf16 v[106:109], v[242:245], v[198:201], v[106:109]
	v_mfma_f32_16x16x32_bf16 v[102:105], v[246:249], v[198:201], v[102:105]
	v_mfma_f32_16x16x32_bf16 v[98:101], v[222:225], v[198:201], v[98:101]
	ds_read_b128 v[198:201], v219 offset:5120
	ds_read_b128 v[182:185], v235 offset:17408
	v_mfma_f32_16x16x32_bf16 v[94:97], v[238:241], v[202:205], v[94:97]
	v_mfma_f32_16x16x32_bf16 v[90:93], v[242:245], v[202:205], v[90:93]
	v_mfma_f32_16x16x32_bf16 v[86:89], v[246:249], v[202:205], v[86:89]
	v_mfma_f32_16x16x32_bf16 v[82:85], v[222:225], v[202:205], v[82:85]
	ds_read_b128 v[202:205], v219 offset:6144
	ds_read_b128 v[186:189], v235 offset:18432
	s_waitcnt lgkmcnt(6)
	v_mfma_f32_16x16x32_bf16 v[78:81], v[238:241], v[206:209], v[78:81]
	v_mfma_f32_16x16x32_bf16 v[74:77], v[242:245], v[206:209], v[74:77]
	v_mfma_f32_16x16x32_bf16 v[70:73], v[246:249], v[206:209], v[70:73]
	v_mfma_f32_16x16x32_bf16 v[66:69], v[222:225], v[206:209], v[66:69]
	ds_read_b128 v[206:209], v219 offset:7168
	ds_read_b128 v[190:193], v235 offset:19456
	s_add_i32 s35, s7, s30
	v_add_u32_e32 v219, s35, v219
	s_waitcnt lgkmcnt(7)
	v_mfma_f32_16x16x32_bf16 v[62:65], v[238:241], v[194:197], v[62:65]
	v_mfma_f32_16x16x32_bf16 v[58:61], v[242:245], v[194:197], v[58:61]
	v_mfma_f32_16x16x32_bf16 v[54:57], v[246:249], v[194:197], v[54:57]
	v_mfma_f32_16x16x32_bf16 v[50:53], v[222:225], v[194:197], v[50:53]
	ds_read_b128 v[194:197], v218
	s_waitcnt vmcnt(0)
	ds_write_b128 v234, v[154:157]
	ds_write_b128 v234, v[158:161] offset:4096
	s_waitcnt lgkmcnt(8)
	v_mfma_f32_16x16x32_bf16 v[46:49], v[238:241], v[198:201], v[46:49]
	v_mfma_f32_16x16x32_bf16 v[42:45], v[242:245], v[198:201], v[42:45]
	v_mfma_f32_16x16x32_bf16 v[38:41], v[246:249], v[198:201], v[38:41]
	v_mfma_f32_16x16x32_bf16 v[34:37], v[222:225], v[198:201], v[34:37]
	ds_read_b128 v[198:201], v218 offset:1024
	ds_write_b128 v234, v[162:165] offset:8192
	ds_write_b128 v234, v[166:169] offset:12288
	s_waitcnt lgkmcnt(9)
	v_mfma_f32_16x16x32_bf16 v[30:33], v[238:241], v[202:205], v[30:33]
	v_mfma_f32_16x16x32_bf16 v[26:29], v[242:245], v[202:205], v[26:29]
	v_mfma_f32_16x16x32_bf16 v[22:25], v[246:249], v[202:205], v[22:25]
	v_mfma_f32_16x16x32_bf16 v[18:21], v[222:225], v[202:205], v[18:21]
	ds_read_b128 v[202:205], v218 offset:2048
	ds_write_b128 v234, v[170:173] offset:16384
	ds_write_b128 v234, v[174:177] offset:20480
	v_add_u32_e32 v234, s31, v234
	s_waitcnt lgkmcnt(10)
	v_mfma_f32_16x16x32_bf16 v[14:17], v[238:241], v[206:209], v[14:17]
	v_mfma_f32_16x16x32_bf16 v[10:13], v[242:245], v[206:209], v[10:13]
	v_mfma_f32_16x16x32_bf16 v[6:9], v[246:249], v[206:209], v[6:9]
	v_mfma_f32_16x16x32_bf16 v[2:5], v[222:225], v[206:209], v[2:5]
	ds_read_b128 v[206:209], v218 offset:3072
	v_add_u32_e32 v235, s30, v235
	s_waitcnt lgkmcnt(1)
	s_barrier
; template <int MODE>
; __device__ void gemm_tile2(const u16* __restrict__ X, int lda, const u16* __restrict__ W, int ldb, int K,
;                            int m0, int n0, u16* __restrict__ outb, int vbase,
;                            const float* resid, float* outf, unsigned char* smem) {
;     ...
;   for (int kt2 = 0; kt2 < nk; kt2 += 2) {
; #pragma unroll
;     for (int h = 0; h < 2; ++h) {
;       const int kt = kt2 + h;
;       const u16* st = sbase + h * G2STAGE;
;       bf16x8 fw[4], fx[4];
; #pragma unroll
;       for (int j = 0; j < 4; ++j) fw[j] = *(const bf16x8*)(st + 256 * G2S + (ww * 64 + j * 16 + l15) * G2S + fsw);
; #pragma unroll
;       for (int i = 0; i < 4; ++i) fx[i] = *(const bf16x8*)(st + (wx * 128 + i * 16 + l15) * G2S + fsw);
;       __builtin_amdgcn_sched_barrier(0);
;       __builtin_amdgcn_s_setprio(1);
; #pragma unroll
;       for (int i = 0; i < 4; ++i) {
; #pragma unroll
;         for (int j = 0; j < 4; ++j) {
;           if (MODE == 1) acc[i][j] = mfma16(fx[i], fw[j], acc[i][j]);
;           else acc[i][j] = mfma16(fw[j], fx[i], acc[i][j]);
;         }
;       }
;       __builtin_amdgcn_s_setprio(0);
;       __builtin_amdgcn_sched_barrier(0);
; #pragma unroll
;       for (int i = 0; i < 4; ++i) fx[i] = *(const bf16x8*)(st + (wx * 128 + (i + 4) * 16 + l15) * G2S + fsw);
;       __builtin_amdgcn_sched_barrier(0);
;       if (kt + 1 < nk) G2_LSTORE(1 - h, 1 - h);
;       if (kt + 3 < nk) G2_GLOAD(1 - h, kt + 3);
;       __builtin_amdgcn_sched_barrier(0);
;       __builtin_amdgcn_s_setprio(1);
; #pragma unroll
;       for (int i = 0; i < 4; ++i) {
; #pragma unroll
;         for (int j = 0; j < 4; ++j) {
;           if (MODE == 1) acc[i + 4][j] = mfma16(fx[i], fw[j], acc[i + 4][j]);
;           else acc[i + 4][j] = mfma16(fw[j], fx[i], acc[i + 4][j]);
;         }
;       }
;       __builtin_amdgcn_s_setprio(0);
;       __syncthreads();
;     }
;   }
	s_mov_b32 s35, s7
	s_mov_b32 s7, s30
	s_mov_b32 s30, s31
	s_mov_b32 s31, s35
	v_mfma_f32_16x16x32_bf16 v[126:129], v[178:181], v[194:197], v[126:129]
	v_mfma_f32_16x16x32_bf16 v[122:125], v[182:185], v[194:197], v[122:125]
	v_mfma_f32_16x16x32_bf16 v[118:121], v[186:189], v[194:197], v[118:121]
	v_mfma_f32_16x16x32_bf16 v[114:117], v[190:193], v[194:197], v[114:117]
	ds_read_b128 v[194:197], v218 offset:4096
	ds_read_b128 v[238:241], v235 offset:16384
	v_mfma_f32_16x16x32_bf16 v[110:113], v[178:181], v[198:201], v[110:113]
	v_mfma_f32_16x16x32_bf16 v[106:109], v[182:185], v[198:201], v[106:109]
	v_mfma_f32_16x16x32_bf16 v[102:105], v[186:189], v[198:201], v[102:105]
	v_mfma_f32_16x16x32_bf16 v[98:101], v[190:193], v[198:201], v[98:101]
	ds_read_b128 v[198:201], v218 offset:5120
	ds_read_b128 v[242:245], v235 offset:17408
	v_mfma_f32_16x16x32_bf16 v[94:97], v[178:181], v[202:205], v[94:97]
	v_mfma_f32_16x16x32_bf16 v[90:93], v[182:185], v[202:205], v[90:93]
	v_mfma_f32_16x16x32_bf16 v[86:89], v[186:189], v[202:205], v[86:89]
	v_mfma_f32_16x16x32_bf16 v[82:85], v[190:193], v[202:205], v[82:85]
	ds_read_b128 v[202:205], v218 offset:6144
	ds_read_b128 v[246:249], v235 offset:18432
	s_waitcnt lgkmcnt(6)
	v_mfma_f32_16x16x32_bf16 v[78:81], v[178:181], v[206:209], v[78:81]
	v_mfma_f32_16x16x32_bf16 v[74:77], v[182:185], v[206:209], v[74:77]
	v_mfma_f32_16x16x32_bf16 v[70:73], v[186:189], v[206:209], v[70:73]
	v_mfma_f32_16x16x32_bf16 v[66:69], v[190:193], v[206:209], v[66:69]
	ds_read_b128 v[206:209], v218 offset:7168
	ds_read_b128 v[222:225], v235 offset:19456
	s_add_i32 s35, s7, s30
	v_add_u32_e32 v218, s35, v218
	s_waitcnt lgkmcnt(7)
	v_mfma_f32_16x16x32_bf16 v[62:65], v[178:181], v[194:197], v[62:65]
	v_mfma_f32_16x16x32_bf16 v[58:61], v[182:185], v[194:197], v[58:61]
	v_mfma_f32_16x16x32_bf16 v[54:57], v[186:189], v[194:197], v[54:57]
	v_mfma_f32_16x16x32_bf16 v[50:53], v[190:193], v[194:197], v[50:53]
	ds_read_b128 v[194:197], v219
	s_waitcnt lgkmcnt(6)
	v_mfma_f32_16x16x32_bf16 v[46:49], v[178:181], v[198:201], v[46:49]
	v_mfma_f32_16x16x32_bf16 v[42:45], v[182:185], v[198:201], v[42:45]
	v_mfma_f32_16x16x32_bf16 v[38:41], v[186:189], v[198:201], v[38:41]
	v_mfma_f32_16x16x32_bf16 v[34:37], v[190:193], v[198:201], v[34:37]
	ds_read_b128 v[198:201], v219 offset:1024
	s_waitcnt lgkmcnt(5)
	v_mfma_f32_16x16x32_bf16 v[30:33], v[178:181], v[202:205], v[30:33]
	v_mfma_f32_16x16x32_bf16 v[26:29], v[182:185], v[202:205], v[26:29]
	v_mfma_f32_16x16x32_bf16 v[22:25], v[186:189], v[202:205], v[22:25]
	v_mfma_f32_16x16x32_bf16 v[18:21], v[190:193], v[202:205], v[18:21]
	ds_read_b128 v[202:205], v219 offset:2048
	s_waitcnt lgkmcnt(4)
	v_mfma_f32_16x16x32_bf16 v[14:17], v[178:181], v[206:209], v[14:17]
	v_mfma_f32_16x16x32_bf16 v[10:13], v[182:185], v[206:209], v[10:13]
	v_mfma_f32_16x16x32_bf16 v[6:9], v[186:189], v[206:209], v[6:9]
	v_mfma_f32_16x16x32_bf16 v[2:5], v[190:193], v[206:209], v[2:5]
	ds_read_b128 v[206:209], v219 offset:3072
	v_add_u32_e32 v235, s30, v235
	s_waitcnt lgkmcnt(1)
	s_barrier
	s_mov_b32 s35, s7
	s_mov_b32 s7, s30
	s_mov_b32 s30, s31
	s_mov_b32 s31, s35
	v_mfma_f32_16x16x32_bf16 v[126:129], v[238:241], v[194:197], v[126:129]
	v_mfma_f32_16x16x32_bf16 v[122:125], v[242:245], v[194:197], v[122:125]
	v_mfma_f32_16x16x32_bf16 v[118:121], v[246:249], v[194:197], v[118:121]
	v_mfma_f32_16x16x32_bf16 v[114:117], v[222:225], v[194:197], v[114:117]
	ds_read_b128 v[194:197], v219 offset:4096
	v_mfma_f32_16x16x32_bf16 v[110:113], v[238:241], v[198:201], v[110:113]
	v_mfma_f32_16x16x32_bf16 v[106:109], v[242:245], v[198:201], v[106:109]
	v_mfma_f32_16x16x32_bf16 v[102:105], v[246:249], v[198:201], v[102:105]
	v_mfma_f32_16x16x32_bf16 v[98:101], v[222:225], v[198:201], v[98:101]
	ds_read_b128 v[198:201], v219 offset:5120
	v_mfma_f32_16x16x32_bf16 v[94:97], v[238:241], v[202:205], v[94:97]
	v_mfma_f32_16x16x32_bf16 v[90:93], v[242:245], v[202:205], v[90:93]
	v_mfma_f32_16x16x32_bf16 v[86:89], v[246:249], v[202:205], v[86:89]
	v_mfma_f32_16x16x32_bf16 v[82:85], v[222:225], v[202:205], v[82:85]
	ds_read_b128 v[202:205], v219 offset:6144
	s_waitcnt lgkmcnt(3)
	v_mfma_f32_16x16x32_bf16 v[78:81], v[238:241], v[206:209], v[78:81]
	v_mfma_f32_16x16x32_bf16 v[74:77], v[242:245], v[206:209], v[74:77]
	v_mfma_f32_16x16x32_bf16 v[70:73], v[246:249], v[206:209], v[70:73]
	v_mfma_f32_16x16x32_bf16 v[66:69], v[222:225], v[206:209], v[66:69]
	ds_read_b128 v[206:209], v219 offset:7168
	s_add_i32 s35, s7, s30
	v_add_u32_e32 v219, s35, v219
	s_waitcnt lgkmcnt(3)
	v_mfma_f32_16x16x32_bf16 v[62:65], v[238:241], v[194:197], v[62:65]
	v_mfma_f32_16x16x32_bf16 v[58:61], v[242:245], v[194:197], v[58:61]
	v_mfma_f32_16x16x32_bf16 v[54:57], v[246:249], v[194:197], v[54:57]
	v_mfma_f32_16x16x32_bf16 v[50:53], v[222:225], v[194:197], v[50:53]
	s_waitcnt lgkmcnt(2)
	v_mfma_f32_16x16x32_bf16 v[46:49], v[238:241], v[198:201], v[46:49]
	v_mfma_f32_16x16x32_bf16 v[42:45], v[242:245], v[198:201], v[42:45]
	v_mfma_f32_16x16x32_bf16 v[38:41], v[246:249], v[198:201], v[38:41]
	v_mfma_f32_16x16x32_bf16 v[34:37], v[222:225], v[198:201], v[34:37]
	s_waitcnt lgkmcnt(1)
	v_mfma_f32_16x16x32_bf16 v[30:33], v[238:241], v[202:205], v[30:33]
	v_mfma_f32_16x16x32_bf16 v[26:29], v[242:245], v[202:205], v[26:29]
	v_mfma_f32_16x16x32_bf16 v[22:25], v[246:249], v[202:205], v[22:25]
	v_mfma_f32_16x16x32_bf16 v[18:21], v[222:225], v[202:205], v[18:21]
	s_waitcnt lgkmcnt(0)
	v_mfma_f32_16x16x32_bf16 v[14:17], v[238:241], v[206:209], v[14:17]
	v_mfma_f32_16x16x32_bf16 v[10:13], v[242:245], v[206:209], v[10:13]
	v_mfma_f32_16x16x32_bf16 v[6:9], v[246:249], v[206:209], v[6:9]
	v_mfma_f32_16x16x32_bf16 v[2:5], v[222:225], v[206:209], v[2:5]
	v_add_u32_e32 v235, s30, v235
	s_barrier
	s_mov_b32 s35, s7
	s_mov_b32 s7, s30
	s_mov_b32 s30, s31
	s_mov_b32 s31, s35
	s_nop 7
